# strategy 2: GLA prep item - gate low-rank tile load no longer waited on its own; its wait and LDS write deferred behind the q/k/v tile loads (one cold round trip less per item), on top of v9
# speedup vs baseline: 1.0107x; 1.0044x over previous
; #define LAS __attribute__((address_space(3)))
; __device__ __forceinline__ float bflo(unsigned w) { return __uint_as_float(w << 16); }
; __device__ __forceinline__ float bfhi(unsigned w) { return __uint_as_float(w & 0xffff0000u); }
; __device__ __forceinline__ void gla_prep_item(Frame& F, const int jl, const int item) {
;     ...
;     if (F.tid < 128) { const int tok = F.tid >> 1, hf = F.tid & 1; const v4u w = *(const v4u*)(P + (row0 + tok) * GLA_NP + G_LR + 8 * hf);
;         LAS float* g = glr + tok * 16 + 8 * hf; g[0] = bflo(w.x); g[1] = bfhi(w.x); g[2] = bflo(w.y); g[3] = bfhi(w.y); g[4] = bflo(w.z); g[5] = bfhi(w.z); g[6] = bflo(w.w); g[7] = bfhi(w.w); }
;     { v4u tq[4], tk[4], tv[6];
; #pragma unroll
;       for (int q = 0; q < 4; ++q) { const int p = F.tid + 512 * q; const bf16* src = P + (row0 + (p >> 5)) * GLA_NP + hh * 256 + 8 * (p & 31); tq[q] = *(const v4u*)(src + G_Q); tk[q] = *(const v4u*)(src + G_K); }
; #pragma unroll
;       for (int q = 0; q < 6; ++q) { const int p = F.tid + 512 * q, tok = p / 48, c = p % 48; tv[q] = *(const v4u*)(P + (row0 + tok) * GLA_NP + G_V + hh * 384 + 8 * c); }
; #pragma unroll
;       for (int q = 0; q < 4; ++q) { const int p = F.tid + 512 * q; *(LAS v4u*)(qs + (p >> 5) * QP + (p & 31) * 16) = tq[q]; *(LAS v4u*)(ks + (p >> 5) * QP + (p & 31) * 16) = tk[q]; }
; #pragma unroll
;       for (int q = 0; q < 6; ++q) { const int p = F.tid + 512 * q, tok = p / 48, c = p % 48; *(LAS v4u*)(vt + tok * VTP + c * 16) = tv[q]; } }
.LBB0_444:
	s_ashr_i32 s0, s64, 8
	s_ashr_i32 s1, s0, 31
	s_lshl_b64 s[0:1], s[0:1], 12
	s_and_b32 s4, s8, 0xfc0
	s_or_b32 s0, s0, s4
	s_and_saveexec_b64 s[4:5], s[40:41]
	s_cbranch_execz .LBB0_446
	v_lshl_add_u64 v[0:1], s[0:1], 0, v[12:13]
	v_mov_b64_e32 v[2:3], s[70:71]
	v_mad_u64_u32 v[2:3], s[10:11], v0, s91, v[2:3]
	v_mov_b32_e32 v0, v3
	v_mad_u64_u32 v[0:1], s[10:11], v1, s91, v[0:1]
	v_mov_b32_e32 v3, v0
	v_mov_b32_e32 v65, v96
	v_lshl_add_u64 v[0:1], v[2:3], 0, v[64:65]
	v_add_co_u32_e32 v0, vcc, 0x2000, v0
	s_nop 1
	v_addc_co_u32_e32 v1, vcc, 0, v1, vcc
	flat_load_dwordx4 v[208:211], v[0:1] offset:2048
.LBB0_446:
	s_or_b64 exec, exec, s[4:5]
	v_lshl_add_u64 v[120:121], s[0:1], 0, v[22:23]
	v_mov_b64_e32 v[136:137], s[70:71]
	v_mad_u64_u32 v[122:123], s[4:5], v120, s91, v[136:137]
	s_and_b32 s9, s64, 3
	v_mov_b32_e32 v120, v123
	s_lshl_b32 s26, s9, 9
	v_mad_u64_u32 v[120:121], s[4:5], v121, s91, v[120:121]
	v_lshl_add_u64 v[112:113], v[48:49], 0, s[26:27]
	v_lshl_add_u64 v[72:73], s[0:1], 0, v[14:15]
	v_lshl_add_u64 v[70:71], s[0:1], 0, v[16:17]
	v_mov_b32_e32 v123, v120
	s_mul_i32 s26, s9, 0x300
	v_lshl_add_u64 v[128:129], s[0:1], 0, v[30:31]
	v_mad_u64_u32 v[4:5], s[4:5], v72, s91, v[112:113]
	v_mad_u64_u32 v[74:75], s[4:5], v70, s91, v[112:113]
	v_lshl_add_u64 v[120:121], v[122:123], 0, s[26:27]
	v_lshl_add_u64 v[122:123], s[0:1], 0, v[26:27]
	v_mad_u64_u32 v[130:131], s[4:5], v128, s91, v[136:137]
	v_mov_b32_e32 v0, v5
	v_mov_b32_e32 v8, v75
	v_mad_u64_u32 v[124:125], s[4:5], v122, s91, v[136:137]
	v_mov_b32_e32 v128, v131
	v_mad_u64_u32 v[0:1], s[4:5], v73, s91, v[0:1]
	v_mad_u64_u32 v[8:9], s[4:5], v71, s91, v[8:9]
	v_mov_b32_e32 v122, v125
	v_mad_u64_u32 v[128:129], s[4:5], v129, s91, v[128:129]
	v_mov_b32_e32 v5, v0
	v_mov_b32_e32 v75, v8
	v_mad_u64_u32 v[122:123], s[4:5], v123, s91, v[122:123]
	v_mov_b32_e32 v131, v128
	v_lshl_add_u64 v[138:139], s[0:1], 0, v[38:39]
	flat_load_dwordx4 v[0:3], v[4:5]
	s_nop 0
	flat_load_dwordx4 v[4:7], v[4:5] offset:2048
	s_nop 0
	flat_load_dwordx4 v[8:11], v[74:75]
	flat_load_dwordx4 v[78:81], v[74:75] offset:2048
	v_lshl_add_u64 v[74:75], s[0:1], 0, v[18:19]
	v_lshl_add_u64 v[120:121], v[24:25], 1, v[120:121]
	v_mov_b32_e32 v125, v122
	v_lshl_add_u64 v[128:129], v[130:131], 0, s[26:27]
	v_lshl_add_u64 v[130:131], s[0:1], 0, v[34:35]
	v_mad_u64_u32 v[140:141], s[4:5], v138, s91, v[136:137]
	v_mad_u64_u32 v[76:77], s[4:5], v74, s91, v[112:113]
	v_add_co_u32_e32 v120, vcc, s30, v120
	v_lshl_add_u64 v[122:123], v[124:125], 0, s[26:27]
	v_mad_u64_u32 v[132:133], s[4:5], v130, s91, v[136:137]
	v_mov_b32_e32 v138, v141
	v_mov_b32_e32 v104, v77
	v_addc_co_u32_e32 v121, vcc, 0, v121, vcc
	v_lshl_add_u64 v[122:123], v[28:29], 1, v[122:123]
	v_mov_b32_e32 v130, v133
	v_mad_u64_u32 v[138:139], s[4:5], v139, s91, v[138:139]
	v_mad_u64_u32 v[104:105], s[4:5], v75, s91, v[104:105]
	v_add_co_u32_e32 v124, vcc, s30, v122
	v_mad_u64_u32 v[130:131], s[4:5], v131, s91, v[130:131]
	v_mov_b32_e32 v141, v138
	v_mov_b32_e32 v77, v104
	v_addc_co_u32_e32 v125, vcc, 0, v123, vcc
	v_lshl_add_u64 v[128:129], v[32:33], 1, v[128:129]
	v_mov_b32_e32 v133, v130
	v_lshl_add_u64 v[138:139], v[140:141], 0, s[26:27]
	v_lshl_add_u64 v[140:141], s[0:1], 0, v[42:43]
	flat_load_dwordx4 v[104:107], v[76:77]
	flat_load_dwordx4 v[108:111], v[76:77] offset:2048
	v_lshl_add_u64 v[76:77], s[0:1], 0, v[20:21]
	v_add_co_u32_e32 v128, vcc, s30, v128
	v_lshl_add_u64 v[130:131], v[132:133], 0, s[26:27]
	v_mad_u64_u32 v[136:137], s[0:1], v140, s91, v[136:137]
	v_addc_co_u32_e32 v129, vcc, 0, v129, vcc
	v_lshl_add_u64 v[130:131], v[36:37], 1, v[130:131]
	v_mov_b32_e32 v140, v137
	v_add_co_u32_e32 v132, vcc, s30, v130
	v_mad_u64_u32 v[140:141], s[0:1], v141, s91, v[140:141]
	s_nop 0
	v_addc_co_u32_e32 v133, vcc, 0, v131, vcc
	v_lshl_add_u64 v[138:139], v[40:41], 1, v[138:139]
	v_mov_b32_e32 v137, v140
	v_mad_u64_u32 v[116:117], s[4:5], v76, s91, v[112:113]
	v_add_co_u32_e32 v138, vcc, s30, v138
	v_lshl_add_u64 v[136:137], v[136:137], 0, s[26:27]
	v_mov_b32_e32 v112, v117
	v_addc_co_u32_e32 v139, vcc, 0, v139, vcc
	v_lshl_add_u64 v[136:137], v[44:45], 1, v[136:137]
	v_mad_u64_u32 v[112:113], s[4:5], v77, s91, v[112:113]
	v_add_co_u32_e32 v140, vcc, s30, v136
	v_mov_b32_e32 v117, v112
	s_nop 0
	v_addc_co_u32_e32 v141, vcc, 0, v137, vcc
	flat_load_dwordx4 v[112:115], v[116:117]
	s_nop 0
	flat_load_dwordx4 v[116:119], v[116:117] offset:2048
	s_nop 0
	flat_load_dwordx4 v[120:123], v[120:121]
	s_nop 0
	flat_load_dwordx4 v[124:127], v[124:125]
	s_nop 0
	flat_load_dwordx4 v[128:131], v[128:129]
	s_nop 0
	flat_load_dwordx4 v[132:135], v[132:133]
	s_nop 0
	flat_load_dwordx4 v[136:139], v[138:139]
	s_nop 0
	flat_load_dwordx4 v[140:143], v[140:141]
	v_add_u32_e32 v65, v83, v46
	s_waitcnt vmcnt(0) lgkmcnt(0)
	s_and_saveexec_b64 s[4:5], s[40:41]
	v_lshlrev_b32_e32 v212, 16, v208
	v_and_b32_e32 v213, 0xffff0000, v208
	v_lshlrev_b32_e32 v214, 16, v209
	v_and_b32_e32 v215, 0xffff0000, v209
	v_lshlrev_b32_e32 v216, 16, v210
	v_and_b32_e32 v217, 0xffff0000, v210
	v_lshlrev_b32_e32 v218, 16, v211
	v_and_b32_e32 v219, 0xffff0000, v211
	ds_write_b128 v82, v[212:215]
	ds_write_b128 v82, v[216:219] offset:16
	s_or_b64 exec, exec, s[4:5]
	ds_write_b128 v65, v[0:3] offset:8192
	ds_write_b128 v65, v[4:7] offset:41984
	v_add_u32_e32 v0, v84, v46
	ds_write_b128 v0, v[8:11] offset:8192
	ds_write_b128 v0, v[78:81] offset:41984
	v_add_u32_e32 v0, v85, v46
	ds_write_b128 v0, v[104:107] offset:8192
	ds_write_b128 v0, v[108:111] offset:41984
	v_add_u32_e32 v0, v86, v46
	ds_write_b128 v0, v[112:115] offset:8192
	ds_write_b128 v0, v[116:119] offset:41984
	ds_write_b128 v47, v[120:123]
	ds_write_b128 v95, v[124:127]
	ds_write_b128 v97, v[128:131]
	ds_write_b128 v98, v[132:135]
	ds_write_b128 v99, v[136:139]
	ds_write_b128 v100, v[140:143]
	v_mov_b64_e32 v[0:1], s[66:67]
	flat_load_dwordx4 v[78:81], v[0:1] offset:40
	s_lshl_b32 s26, s9, 10
	v_mov_b32_e32 v67, v96
	s_movk_i32 s0, 0x3000
	s_lshl_b32 s4, s9, 8
	s_waitcnt vmcnt(0) lgkmcnt(0)
; #define LAS __attribute__((address_space(3)))
; __device__ __forceinline__ float log_sigmoid(float x) { return fminf(x, 0.f) - __logf(1.0f + __expf(-fabsf(x))); }
; __device__ __forceinline__ void gla_prep_item(Frame& F, const int jl, const int item) {
;     ...
;     float wg[16];
; #pragma unroll
;     for (int rr = 0; rr < 16; ++rr) wg[rr] = F.in[5][(size_t)jl * 16 * 1024 + rr * 1024 + hh * 256 + d];
;     const float bg = F.in[6][jl * 1024 + hh * 256 + d];
;     __syncthreads();
;     float cum[32]; float run = 0.f;
; #pragma unroll
;     for (int t = 0; t < 32; ++t) { const LAS f32x4* g4 = (const LAS f32x4*)(glr + (half * 32 + t) * 16); float pre = bg;
; #pragma unroll
;         for (int r4 = 0; r4 < 4; ++r4) { const f32x4 g = g4[r4]; pre += g.x * wg[4 * r4] + g.y * wg[4 * r4 + 1] + g.z * wg[4 * r4 + 2] + g.w * wg[4 * r4 + 3]; }
;         run += log_sigmoid(pre) * 0.0625f; cum[t] = run; }
	v_lshl_add_u64 v[0:1], v[78:79], 0, s[72:73]
	v_lshl_add_u64 v[0:1], v[0:1], 0, s[26:27]
	v_lshl_add_u64 v[104:105], v[0:1], 0, v[66:67]
	v_add_co_u32_e32 v0, vcc, s30, v104
	s_nop 1
	v_addc_co_u32_e32 v1, vcc, 0, v105, vcc
	v_add_co_u32_e32 v2, vcc, s3, v104
	s_nop 1
	v_addc_co_u32_e32 v3, vcc, 0, v105, vcc
	v_add_co_u32_e32 v8, vcc, s0, v104
	s_movk_i32 s0, 0x4000
	s_nop 0
	v_addc_co_u32_e32 v9, vcc, 0, v105, vcc
	v_add_co_u32_e32 v10, vcc, s0, v104
	s_movk_i32 s0, 0x5000
	s_nop 0
	v_addc_co_u32_e32 v11, vcc, 0, v105, vcc
	v_add_co_u32_e32 v78, vcc, s0, v104
	s_movk_i32 s0, 0x6000
	s_nop 0
	v_addc_co_u32_e32 v79, vcc, 0, v105, vcc
	v_add_co_u32_e32 v106, vcc, s0, v104
	s_movk_i32 s0, 0x7000
	s_nop 0
	v_addc_co_u32_e32 v107, vcc, 0, v105, vcc
	v_add_co_u32_e32 v108, vcc, s0, v104
	s_mov_b32 s0, 0x8000
	s_nop 0
	v_addc_co_u32_e32 v109, vcc, 0, v105, vcc
	flat_load_dword v4, v[104:105]
	flat_load_dword v6, v[0:1]
	s_nop 0
	flat_load_dword v2, v[2:3]
	s_nop 0
	flat_load_dword v0, v[8:9]
	flat_load_dword v5, v[10:11]
	flat_load_dword v7, v[78:79]
	flat_load_dword v3, v[106:107]
	flat_load_dword v1, v[108:109]
	v_add_co_u32_e32 v8, vcc, s0, v104
	s_mov_b32 s0, 0x9000
	s_nop 0
	v_addc_co_u32_e32 v9, vcc, 0, v105, vcc
	v_add_co_u32_e32 v78, vcc, s0, v104
	s_mov_b32 s0, 0xa000
	s_nop 0
	v_addc_co_u32_e32 v79, vcc, 0, v105, vcc
	v_add_co_u32_e32 v106, vcc, s0, v104
	s_mov_b32 s0, 0xb000
	s_nop 0
	v_addc_co_u32_e32 v107, vcc, 0, v105, vcc
	v_add_co_u32_e32 v108, vcc, s0, v104
	s_mov_b32 s0, 0xc000
	s_nop 0
	v_addc_co_u32_e32 v109, vcc, 0, v105, vcc
	v_add_co_u32_e32 v110, vcc, s0, v104
	s_mov_b32 s0, 0xd000
	s_nop 0
	v_addc_co_u32_e32 v111, vcc, 0, v105, vcc
	v_add_co_u32_e32 v112, vcc, s0, v104
	s_mov_b32 s0, 0xe000
	s_nop 0
	v_addc_co_u32_e32 v113, vcc, 0, v105, vcc
	v_add_co_u32_e32 v114, vcc, s0, v104
	s_mov_b32 s0, 0xf000
	s_nop 0
	v_addc_co_u32_e32 v115, vcc, 0, v105, vcc
	flat_load_dword v10, v[8:9]
	s_nop 0
	flat_load_dword v78, v[78:79]
	s_nop 0
	flat_load_dword v8, v[106:107]
	flat_load_dword v11, v[110:111]
	flat_load_dword v79, v[112:113]
	flat_load_dword v9, v[114:115]
	v_or_b32_e32 v106, s4, v87
	v_mov_b32_e32 v107, v96
	v_add_co_u32_e32 v104, vcc, s0, v104
	v_lshl_add_u64 v[80:81], v[106:107], 2, v[80:81]
	s_nop 0
	v_addc_co_u32_e32 v105, vcc, 0, v105, vcc
	flat_load_dword v65, v[80:81]
	s_nop 0
	flat_load_dword v81, v[104:105]
	flat_load_dword v80, v[108:109]
	s_waitcnt lgkmcnt(0)
	s_barrier
	ds_read_b128 v[104:107], v88
	ds_read_b128 v[108:111], v88 offset:16
	ds_read_b128 v[112:115], v88 offset:32
	ds_read_b128 v[116:119], v88 offset:48
	s_mov_b32 s0, 0x3d800000
	s_waitcnt lgkmcnt(0)
	v_mov_b32_e32 v120, v104
	v_mov_b32_e32 v121, v108
	v_mov_b32_e32 v108, v105
	v_mov_b32_e32 v104, v106
	v_mov_b32_e32 v105, v110
	v_mov_b32_e32 v110, v107
	v_mov_b32_e32 v107, v116
	v_mov_b32_e32 v116, v113
	v_mov_b32_e32 v106, v112
	v_mov_b32_e32 v112, v114
	v_mov_b32_e32 v113, v118
	v_mov_b32_e32 v118, v115
	s_waitcnt vmcnt(0)
	v_pk_mul_f32 v[108:109], v[6:7], v[108:109]
	s_nop 0
	v_pk_fma_f32 v[108:109], v[4:5], v[120:121], v[108:109]
	v_pk_mul_f32 v[114:115], v[78:79], v[116:117]
	v_pk_fma_f32 v[104:105], v[2:3], v[104:105], v[108:109]
	v_pk_fma_f32 v[106:107], v[10:11], v[106:107], v[114:115]
	v_pk_fma_f32 v[104:105], v[0:1], v[110:111], v[104:105]
	v_pk_fma_f32 v[106:107], v[8:9], v[112:113], v[106:107]
	v_add_f32_e32 v67, v65, v104
	v_add_f32_e32 v67, v67, v105
	v_pk_fma_f32 v[104:105], v[80:81], v[118:119], v[106:107]
	s_nop 0
	v_add_f32_e32 v67, v67, v104
	v_add_f32_e32 v67, v67, v105
	v_mul_f32_e64 v69, |v67|, s31
	v_exp_f32_e32 v69, v69
	ds_read_b128 v[104:107], v88 offset:64
	v_min_f32_e32 v67, 0, v67
	v_add_f32_e32 v69, 1.0, v69
	v_cmp_gt_f32_e32 vcc, s34, v69
	s_nop 1
	v_cndmask_b32_e64 v108, 0, 32, vcc
	v_ldexp_f32 v69, v69, v108
	ds_read_b128 v[108:111], v88 offset:80
	v_log_f32_e32 v69, v69
	s_waitcnt lgkmcnt(1)
	v_mov_b32_e32 v112, v104
	v_mul_f32_e32 v104, 0x3f317217, v69
	s_waitcnt lgkmcnt(0)
	v_mov_b32_e32 v113, v108
	v_mov_b32_e32 v108, v105
	v_fma_f32 v116, v69, s35, -v104
	v_pk_mul_f32 v[104:105], v[6:7], v[108:109]
	v_mov_b32_e32 v108, v106
	v_pk_fma_f32 v[104:105], v[4:5], v[112:113], v[104:105]
	v_mov_b32_e32 v109, v110
	v_pk_fma_f32 v[108:109], v[2:3], v[108:109], v[104:105]
	v_mov_b32_e32 v110, v107
	ds_read_b128 v[104:107], v88 offset:96
	ds_read_b128 v[112:115], v88 offset:112
	v_pk_fma_f32 v[108:109], v[0:1], v[110:111], v[108:109]
	v_fmac_f32_e32 v116, 0x3377d1cf, v69
	v_add_f32_e32 v108, v65, v108
	v_add_f32_e32 v110, v108, v109
	s_waitcnt lgkmcnt(0)
	v_mov_b32_e32 v109, v112
	v_mov_b32_e32 v112, v105
	v_mov_b32_e32 v108, v104
	v_pk_mul_f32 v[104:105], v[78:79], v[112:113]
	v_fmac_f32_e32 v116, 0x3f317217, v69
	v_pk_fma_f32 v[104:105], v[10:11], v[108:109], v[104:105]
	v_mov_b32_e32 v108, v106
	v_mov_b32_e32 v109, v114
	v_pk_fma_f32 v[104:105], v[8:9], v[108:109], v[104:105]
	v_mov_b32_e32 v114, v107
	v_pk_fma_f32 v[104:105], v[80:81], v[114:115], v[104:105]
	v_cmp_lt_f32_e64 s[62:63], |v69|, s20
	v_add_f32_e32 v104, v110, v104
	v_add_f32_e32 v105, v104, v105
	v_mul_f32_e64 v104, |v105|, s31
	v_exp_f32_e32 v104, v104
	v_cndmask_b32_e64 v69, v69, v116, s[62:63]
	v_cndmask_b32_e32 v106, 0, v244, vcc
	v_sub_f32_e32 v69, v69, v106
	v_add_f32_e32 v104, 1.0, v104
	v_cmp_gt_f32_e32 vcc, s34, v104
	v_sub_f32_e32 v67, v67, v69
	s_nop 0
	v_cndmask_b32_e64 v106, 0, 32, vcc
	v_ldexp_f32 v104, v104, v106
	ds_read_b128 v[106:109], v88 offset:128
	ds_read_b128 v[110:113], v88 offset:144
	v_log_f32_e32 v118, v104
	v_fma_f32 v104, v67, s0, 0
	v_min_f32_e32 v67, 0, v105
	s_waitcnt lgkmcnt(1)
	v_mov_b32_e32 v114, v106
	s_waitcnt lgkmcnt(0)
; #define LAS __attribute__((address_space(3)))
; __device__ __forceinline__ float log_sigmoid(float x) { return fminf(x, 0.f) - __logf(1.0f + __expf(-fabsf(x))); }
; __device__ __forceinline__ void gla_prep_item(Frame& F, const int jl, const int item) {
;     ...
;     float cum[32]; float run = 0.f;
; #pragma unroll
;     for (int t = 0; t < 32; ++t) { const LAS f32x4* g4 = (const LAS f32x4*)(glr + (half * 32 + t) * 16); float pre = bg;
; #pragma unroll
;         for (int r4 = 0; r4 < 4; ++r4) { const f32x4 g = g4[r4]; pre += g.x * wg[4 * r4] + g.y * wg[4 * r4 + 1] + g.z * wg[4 * r4 + 2] + g.w * wg[4 * r4 + 3]; }
;         run += log_sigmoid(pre) * 0.0625f; cum[t] = run; }
	v_mov_b32_e32 v115, v110
	v_mov_b32_e32 v110, v107
	v_pk_mul_f32 v[106:107], v[6:7], v[110:111]
	v_mov_b32_e32 v110, v108
	v_pk_fma_f32 v[106:107], v[4:5], v[114:115], v[106:107]
	v_mov_b32_e32 v111, v112
	v_pk_fma_f32 v[110:111], v[2:3], v[110:111], v[106:107]
	v_mov_b32_e32 v112, v109
	ds_read_b128 v[106:109], v88 offset:160
	ds_read_b128 v[114:117], v88 offset:176
	v_pk_fma_f32 v[110:111], v[0:1], v[112:113], v[110:111]
	v_mul_f32_e32 v69, 0x3f317217, v118
	v_add_f32_e32 v105, v65, v110
	v_add_f32_e32 v105, v105, v111
	s_waitcnt lgkmcnt(0)
	v_mov_b32_e32 v111, v114
	v_mov_b32_e32 v114, v107
	v_mov_b32_e32 v110, v106
	v_pk_mul_f32 v[106:107], v[78:79], v[114:115]
	v_fma_f32 v69, v118, s35, -v69
	v_pk_fma_f32 v[106:107], v[10:11], v[110:111], v[106:107]
	v_mov_b32_e32 v110, v108
	v_mov_b32_e32 v111, v116
	v_pk_fma_f32 v[106:107], v[8:9], v[110:111], v[106:107]
	v_mov_b32_e32 v116, v109
	v_pk_fma_f32 v[106:107], v[80:81], v[116:117], v[106:107]
	v_fmac_f32_e32 v69, 0x3377d1cf, v118
	v_add_f32_e32 v105, v105, v106
	v_add_f32_e32 v105, v105, v107
	v_mul_f32_e64 v106, |v105|, s31
	v_exp_f32_e32 v106, v106
	v_fmac_f32_e32 v69, 0x3f317217, v118
	v_cmp_lt_f32_e64 s[62:63], |v118|, s20
	v_cndmask_b32_e32 v107, 0, v244, vcc
	v_add_f32_e32 v106, 1.0, v106
	v_cndmask_b32_e64 v69, v118, v69, s[62:63]
	v_cmp_gt_f32_e32 vcc, s34, v106
	v_sub_f32_e32 v69, v69, v107
	v_sub_f32_e32 v67, v67, v69
	v_cndmask_b32_e64 v107, 0, 32, vcc
	v_ldexp_f32 v106, v106, v107
	v_log_f32_e32 v118, v106
	ds_read_b128 v[106:109], v88 offset:192
	ds_read_b128 v[110:113], v88 offset:208
	v_min_f32_e32 v69, 0, v105
	v_fmamk_f32 v67, v67, 0x3d800000, v104
	v_mul_f32_e32 v105, 0x3f317217, v118
	s_waitcnt lgkmcnt(1)
	v_mov_b32_e32 v114, v106
	s_waitcnt lgkmcnt(0)
	v_mov_b32_e32 v115, v110
	v_mov_b32_e32 v110, v107
	v_pk_mul_f32 v[106:107], v[6:7], v[110:111]
	v_mov_b32_e32 v110, v108
	v_pk_fma_f32 v[106:107], v[4:5], v[114:115], v[106:107]
	v_mov_b32_e32 v111, v112
	v_pk_fma_f32 v[110:111], v[2:3], v[110:111], v[106:107]
	v_mov_b32_e32 v112, v109
	ds_read_b128 v[106:109], v88 offset:224
	ds_read_b128 v[114:117], v88 offset:240
	v_pk_fma_f32 v[110:111], v[0:1], v[112:113], v[110:111]
	v_fma_f32 v105, v118, s35, -v105
	v_add_f32_e32 v110, v65, v110
	v_add_f32_e32 v112, v110, v111
	s_waitcnt lgkmcnt(0)
	v_mov_b32_e32 v111, v114
	v_mov_b32_e32 v114, v107
	v_mov_b32_e32 v110, v106
	v_pk_mul_f32 v[106:107], v[78:79], v[114:115]
	v_fmac_f32_e32 v105, 0x3377d1cf, v118
	v_pk_fma_f32 v[106:107], v[10:11], v[110:111], v[106:107]
	v_mov_b32_e32 v110, v108
	v_mov_b32_e32 v111, v116
	v_pk_fma_f32 v[106:107], v[8:9], v[110:111], v[106:107]
	v_mov_b32_e32 v116, v109
	v_pk_fma_f32 v[106:107], v[80:81], v[116:117], v[106:107]
	v_fmac_f32_e32 v105, 0x3f317217, v118
	v_add_f32_e32 v106, v112, v106
	v_add_f32_e32 v106, v106, v107
	v_mul_f32_e64 v107, |v106|, s31
	v_exp_f32_e32 v107, v107
	v_cmp_lt_f32_e64 s[62:63], |v118|, s20
	v_cndmask_b32_e32 v108, 0, v244, vcc
	s_mov_b32 s0, 0x2b700000
	v_add_f32_e32 v107, 1.0, v107
	v_cndmask_b32_e64 v105, v118, v105, s[62:63]
	v_cmp_gt_f32_e32 vcc, s34, v107
	v_sub_f32_e32 v105, v105, v108
	v_sub_f32_e32 v69, v69, v105
	v_cndmask_b32_e64 v108, 0, 32, vcc
	v_ldexp_f32 v107, v107, v108
	v_log_f32_e32 v118, v107
	v_min_f32_e32 v105, 0, v106
	ds_read_b128 v[106:109], v88 offset:256
	ds_read_b128 v[110:113], v88 offset:272
	v_fmamk_f32 v69, v69, 0x3d800000, v67
	v_mul_f32_e32 v114, 0x3f317217, v118
	v_fma_f32 v119, v118, s35, -v114
	s_waitcnt lgkmcnt(1)
	v_mov_b32_e32 v114, v106
	s_waitcnt lgkmcnt(0)
	v_mov_b32_e32 v115, v110
	v_mov_b32_e32 v110, v107
	v_pk_mul_f32 v[106:107], v[6:7], v[110:111]
	v_mov_b32_e32 v110, v108
	v_pk_fma_f32 v[106:107], v[4:5], v[114:115], v[106:107]
	v_mov_b32_e32 v111, v112
	v_pk_fma_f32 v[110:111], v[2:3], v[110:111], v[106:107]
	v_mov_b32_e32 v112, v109
	ds_read_b128 v[106:109], v88 offset:288
	ds_read_b128 v[114:117], v88 offset:304
	v_pk_fma_f32 v[110:111], v[0:1], v[112:113], v[110:111]
	v_fmac_f32_e32 v119, 0x3377d1cf, v118
	v_add_f32_e32 v110, v65, v110
	v_add_f32_e32 v112, v110, v111
	s_waitcnt lgkmcnt(0)
	v_mov_b32_e32 v111, v114
	v_mov_b32_e32 v114, v107
	v_mov_b32_e32 v110, v106
	v_pk_mul_f32 v[106:107], v[78:79], v[114:115]
	v_fmac_f32_e32 v119, 0x3f317217, v118
	v_pk_fma_f32 v[106:107], v[10:11], v[110:111], v[106:107]
	v_mov_b32_e32 v110, v108
	v_mov_b32_e32 v111, v116
	v_pk_fma_f32 v[106:107], v[8:9], v[110:111], v[106:107]
	v_mov_b32_e32 v116, v109
	v_pk_fma_f32 v[106:107], v[80:81], v[116:117], v[106:107]
	v_cmp_lt_f32_e64 s[62:63], |v118|, s20
	v_add_f32_e32 v106, v112, v106
	v_add_f32_e32 v106, v106, v107
	v_mul_f32_e64 v107, |v106|, s31
	v_exp_f32_e32 v107, v107
	v_cndmask_b32_e64 v108, v118, v119, s[62:63]
	v_cndmask_b32_e32 v109, 0, v244, vcc
	v_sub_f32_e32 v108, v108, v109
	v_add_f32_e32 v107, 1.0, v107
	v_cmp_gt_f32_e32 vcc, s34, v107
	v_sub_f32_e32 v105, v105, v108
	v_min_f32_e32 v119, 0, v106
	v_cndmask_b32_e64 v109, 0, 32, vcc
	v_ldexp_f32 v107, v107, v109
	v_log_f32_e32 v118, v107
	ds_read_b128 v[106:109], v88 offset:320
	ds_read_b128 v[110:113], v88 offset:336
	v_fmamk_f32 v105, v105, 0x3d800000, v69
	v_mul_f32_e32 v114, 0x3f317217, v118
	v_fma_f32 v120, v118, s35, -v114
	s_waitcnt lgkmcnt(0)
	v_mov_b32_e32 v115, v110
	v_mov_b32_e32 v110, v107
	v_mov_b32_e32 v114, v106
	v_pk_mul_f32 v[106:107], v[6:7], v[110:111]
	v_mov_b32_e32 v110, v108
	v_pk_fma_f32 v[106:107], v[4:5], v[114:115], v[106:107]
	v_mov_b32_e32 v111, v112
	v_pk_fma_f32 v[110:111], v[2:3], v[110:111], v[106:107]
	v_mov_b32_e32 v112, v109
	ds_read_b128 v[106:109], v88 offset:352
	ds_read_b128 v[114:117], v88 offset:368
	v_pk_fma_f32 v[110:111], v[0:1], v[112:113], v[110:111]
	v_fmac_f32_e32 v120, 0x3377d1cf, v118
	v_add_f32_e32 v110, v65, v110
	v_add_f32_e32 v112, v110, v111
	s_waitcnt lgkmcnt(0)
; #define LAS __attribute__((address_space(3)))
; __device__ __forceinline__ float log_sigmoid(float x) { return fminf(x, 0.f) - __logf(1.0f + __expf(-fabsf(x))); }
; __device__ __forceinline__ void gla_prep_item(Frame& F, const int jl, const int item) {
;     ...
;     float cum[32]; float run = 0.f;
; #pragma unroll
;     for (int t = 0; t < 32; ++t) { const LAS f32x4* g4 = (const LAS f32x4*)(glr + (half * 32 + t) * 16); float pre = bg;
; #pragma unroll
;         for (int r4 = 0; r4 < 4; ++r4) { const f32x4 g = g4[r4]; pre += g.x * wg[4 * r4] + g.y * wg[4 * r4 + 1] + g.z * wg[4 * r4 + 2] + g.w * wg[4 * r4 + 3]; }
;         run += log_sigmoid(pre) * 0.0625f; cum[t] = run; }
	v_mov_b32_e32 v111, v114
	v_mov_b32_e32 v114, v107
	v_mov_b32_e32 v110, v106
	v_pk_mul_f32 v[106:107], v[78:79], v[114:115]
	v_fmac_f32_e32 v120, 0x3f317217, v118
	v_pk_fma_f32 v[106:107], v[10:11], v[110:111], v[106:107]
	v_mov_b32_e32 v110, v108
	v_mov_b32_e32 v111, v116
	v_pk_fma_f32 v[106:107], v[8:9], v[110:111], v[106:107]
	v_mov_b32_e32 v116, v109
	v_pk_fma_f32 v[106:107], v[80:81], v[116:117], v[106:107]
	v_cmp_lt_f32_e64 s[62:63], |v118|, s20
	v_add_f32_e32 v106, v112, v106
	v_add_f32_e32 v107, v106, v107
	v_mul_f32_e64 v106, |v107|, s31
	v_exp_f32_e32 v106, v106
	v_cndmask_b32_e64 v108, v118, v120, s[62:63]
	v_cndmask_b32_e32 v109, 0, v244, vcc
	v_sub_f32_e32 v108, v108, v109
	v_add_f32_e32 v106, 1.0, v106
	v_cmp_gt_f32_e32 vcc, s34, v106
	v_min_f32_e32 v107, 0, v107
	s_nop 0
	v_cndmask_b32_e64 v109, 0, 32, vcc
	v_ldexp_f32 v106, v106, v109
	v_log_f32_e32 v120, v106
	v_sub_f32_e32 v106, v119, v108
	ds_read_b128 v[108:111], v88 offset:384
	ds_read_b128 v[112:115], v88 offset:400
	v_fmamk_f32 v106, v106, 0x3d800000, v105
	v_mul_f32_e32 v116, 0x3f317217, v120
	v_fma_f32 v121, v120, s35, -v116
	s_waitcnt lgkmcnt(1)
	v_mov_b32_e32 v116, v108
	s_waitcnt lgkmcnt(0)
	v_mov_b32_e32 v117, v112
	v_mov_b32_e32 v112, v109
	v_pk_mul_f32 v[108:109], v[6:7], v[112:113]
	v_mov_b32_e32 v112, v110
	v_pk_fma_f32 v[108:109], v[4:5], v[116:117], v[108:109]
	v_mov_b32_e32 v113, v114
	v_pk_fma_f32 v[112:113], v[2:3], v[112:113], v[108:109]
	v_mov_b32_e32 v114, v111
	ds_read_b128 v[108:111], v88 offset:416
	ds_read_b128 v[116:119], v88 offset:432
	v_pk_fma_f32 v[112:113], v[0:1], v[114:115], v[112:113]
	v_fmac_f32_e32 v121, 0x3377d1cf, v120
	v_add_f32_e32 v112, v65, v112
	v_add_f32_e32 v114, v112, v113
	s_waitcnt lgkmcnt(0)
	v_mov_b32_e32 v113, v116
	v_mov_b32_e32 v116, v109
	v_mov_b32_e32 v112, v108
	v_pk_mul_f32 v[108:109], v[78:79], v[116:117]
	v_fmac_f32_e32 v121, 0x3f317217, v120
	v_pk_fma_f32 v[108:109], v[10:11], v[112:113], v[108:109]
	v_mov_b32_e32 v112, v110
	v_mov_b32_e32 v113, v118
	v_pk_fma_f32 v[108:109], v[8:9], v[112:113], v[108:109]
	v_mov_b32_e32 v118, v111
	v_pk_fma_f32 v[108:109], v[80:81], v[118:119], v[108:109]
	v_cmp_lt_f32_e64 s[62:63], |v120|, s20
	v_add_f32_e32 v108, v114, v108
	v_add_f32_e32 v108, v108, v109
	v_mul_f32_e64 v109, |v108|, s31
	v_exp_f32_e32 v109, v109
	v_cndmask_b32_e64 v110, v120, v121, s[62:63]
	v_cndmask_b32_e32 v111, 0, v244, vcc
	v_sub_f32_e32 v110, v110, v111
	v_add_f32_e32 v109, 1.0, v109
	v_cmp_gt_f32_e32 vcc, s34, v109
	v_sub_f32_e32 v107, v107, v110
	v_min_f32_e32 v121, 0, v108
	v_cndmask_b32_e64 v111, 0, 32, vcc
	v_ldexp_f32 v109, v109, v111
	v_log_f32_e32 v120, v109
	ds_read_b128 v[108:111], v88 offset:448
	ds_read_b128 v[112:115], v88 offset:464
	v_fmamk_f32 v107, v107, 0x3d800000, v106
	v_mul_f32_e32 v116, 0x3f317217, v120
	v_fma_f32 v122, v120, s35, -v116
	s_waitcnt lgkmcnt(0)
	v_mov_b32_e32 v117, v112
	v_mov_b32_e32 v112, v109
	v_mov_b32_e32 v116, v108
	v_pk_mul_f32 v[108:109], v[6:7], v[112:113]
	v_mov_b32_e32 v112, v110
	v_pk_fma_f32 v[108:109], v[4:5], v[116:117], v[108:109]
	v_mov_b32_e32 v113, v114
	v_pk_fma_f32 v[112:113], v[2:3], v[112:113], v[108:109]
	v_mov_b32_e32 v114, v111
	ds_read_b128 v[108:111], v88 offset:480
	ds_read_b128 v[116:119], v88 offset:496
	v_pk_fma_f32 v[112:113], v[0:1], v[114:115], v[112:113]
	v_fmac_f32_e32 v122, 0x3377d1cf, v120
	v_add_f32_e32 v112, v65, v112
	v_add_f32_e32 v114, v112, v113
	s_waitcnt lgkmcnt(0)
	v_mov_b32_e32 v113, v116
	v_mov_b32_e32 v116, v109
	v_mov_b32_e32 v112, v108
	v_pk_mul_f32 v[108:109], v[78:79], v[116:117]
	v_fmac_f32_e32 v122, 0x3f317217, v120
	v_pk_fma_f32 v[108:109], v[10:11], v[112:113], v[108:109]
	v_mov_b32_e32 v112, v110
	v_mov_b32_e32 v113, v118
	v_pk_fma_f32 v[108:109], v[8:9], v[112:113], v[108:109]
	v_mov_b32_e32 v118, v111
	v_pk_fma_f32 v[108:109], v[80:81], v[118:119], v[108:109]
	v_cmp_lt_f32_e64 s[62:63], |v120|, s20
	v_add_f32_e32 v108, v114, v108
	v_add_f32_e32 v109, v108, v109
	v_mul_f32_e64 v108, |v109|, s31
	v_exp_f32_e32 v108, v108
	v_cndmask_b32_e64 v110, v120, v122, s[62:63]
	v_cndmask_b32_e32 v111, 0, v244, vcc
	v_sub_f32_e32 v110, v110, v111
	v_add_f32_e32 v108, 1.0, v108
	v_cmp_gt_f32_e32 vcc, s34, v108
	v_min_f32_e32 v109, 0, v109
	s_nop 0
	v_cndmask_b32_e64 v111, 0, 32, vcc
	v_ldexp_f32 v108, v108, v111
	v_log_f32_e32 v122, v108
	v_sub_f32_e32 v108, v121, v110
	ds_read_b128 v[110:113], v88 offset:512
	ds_read_b128 v[114:117], v88 offset:528
	v_fmamk_f32 v108, v108, 0x3d800000, v107
	v_mul_f32_e32 v118, 0x3f317217, v122
	v_fma_f32 v123, v122, s35, -v118
	s_waitcnt lgkmcnt(1)
	v_mov_b32_e32 v118, v110
	s_waitcnt lgkmcnt(0)
	v_mov_b32_e32 v119, v114
	v_mov_b32_e32 v114, v111
	v_pk_mul_f32 v[110:111], v[6:7], v[114:115]
	v_mov_b32_e32 v114, v112
	v_pk_fma_f32 v[110:111], v[4:5], v[118:119], v[110:111]
	v_mov_b32_e32 v115, v116
	v_pk_fma_f32 v[114:115], v[2:3], v[114:115], v[110:111]
	v_mov_b32_e32 v116, v113
	ds_read_b128 v[110:113], v88 offset:544
	ds_read_b128 v[118:121], v88 offset:560
	v_pk_fma_f32 v[114:115], v[0:1], v[116:117], v[114:115]
	v_fmac_f32_e32 v123, 0x3377d1cf, v122
	v_add_f32_e32 v114, v65, v114
	v_add_f32_e32 v116, v114, v115
	s_waitcnt lgkmcnt(0)
; #define LAS __attribute__((address_space(3)))
; __device__ __forceinline__ float log_sigmoid(float x) { return fminf(x, 0.f) - __logf(1.0f + __expf(-fabsf(x))); }
; __device__ __forceinline__ void gla_prep_item(Frame& F, const int jl, const int item) {
;     ...
;     float cum[32]; float run = 0.f;
; #pragma unroll
;     for (int t = 0; t < 32; ++t) { const LAS f32x4* g4 = (const LAS f32x4*)(glr + (half * 32 + t) * 16); float pre = bg;
; #pragma unroll
;         for (int r4 = 0; r4 < 4; ++r4) { const f32x4 g = g4[r4]; pre += g.x * wg[4 * r4] + g.y * wg[4 * r4 + 1] + g.z * wg[4 * r4 + 2] + g.w * wg[4 * r4 + 3]; }
;         run += log_sigmoid(pre) * 0.0625f; cum[t] = run; }
	v_mov_b32_e32 v115, v118
	v_mov_b32_e32 v118, v111
	v_mov_b32_e32 v114, v110
	v_pk_mul_f32 v[110:111], v[78:79], v[118:119]
	v_fmac_f32_e32 v123, 0x3f317217, v122
	v_pk_fma_f32 v[110:111], v[10:11], v[114:115], v[110:111]
	v_mov_b32_e32 v114, v112
	v_mov_b32_e32 v115, v120
	v_pk_fma_f32 v[110:111], v[8:9], v[114:115], v[110:111]
	v_mov_b32_e32 v120, v113
	v_pk_fma_f32 v[110:111], v[80:81], v[120:121], v[110:111]
	v_cmp_lt_f32_e64 s[62:63], |v122|, s20
	v_add_f32_e32 v110, v116, v110
	v_add_f32_e32 v111, v110, v111
	v_mul_f32_e64 v110, |v111|, s31
	v_exp_f32_e32 v110, v110
	v_cndmask_b32_e64 v112, v122, v123, s[62:63]
	v_cndmask_b32_e32 v113, 0, v244, vcc
	v_sub_f32_e32 v112, v112, v113
	v_add_f32_e32 v110, 1.0, v110
	v_cmp_gt_f32_e32 vcc, s34, v110
	v_sub_f32_e32 v109, v109, v112
	s_nop 0
	v_cndmask_b32_e64 v113, 0, 32, vcc
	v_ldexp_f32 v110, v110, v113
	ds_read_b128 v[112:115], v88 offset:576
	ds_read_b128 v[116:119], v88 offset:592
	v_log_f32_e32 v124, v110
	v_fmamk_f32 v110, v109, 0x3d800000, v108
	v_min_f32_e32 v109, 0, v111
	s_waitcnt lgkmcnt(1)
	v_mov_b32_e32 v120, v112
	s_waitcnt lgkmcnt(0)
	v_mov_b32_e32 v121, v116
	v_mov_b32_e32 v116, v113
	v_pk_mul_f32 v[112:113], v[6:7], v[116:117]
	v_mov_b32_e32 v116, v114
	v_pk_fma_f32 v[112:113], v[4:5], v[120:121], v[112:113]
	v_mov_b32_e32 v117, v118
	v_pk_fma_f32 v[116:117], v[2:3], v[116:117], v[112:113]
	v_mov_b32_e32 v118, v115
	ds_read_b128 v[112:115], v88 offset:608
	ds_read_b128 v[120:123], v88 offset:624
	v_pk_fma_f32 v[116:117], v[0:1], v[118:119], v[116:117]
	v_mul_f32_e32 v111, 0x3f317217, v124
	v_add_f32_e32 v116, v65, v116
	v_add_f32_e32 v118, v116, v117
	s_waitcnt lgkmcnt(0)
	v_mov_b32_e32 v117, v120
	v_mov_b32_e32 v120, v113
	v_mov_b32_e32 v116, v112
	v_pk_mul_f32 v[112:113], v[78:79], v[120:121]
	v_fma_f32 v111, v124, s35, -v111
	v_pk_fma_f32 v[112:113], v[10:11], v[116:117], v[112:113]
	v_mov_b32_e32 v116, v114
	v_mov_b32_e32 v117, v122
	v_pk_fma_f32 v[112:113], v[8:9], v[116:117], v[112:113]
	v_mov_b32_e32 v122, v115
	v_pk_fma_f32 v[112:113], v[80:81], v[122:123], v[112:113]
	v_fmac_f32_e32 v111, 0x3377d1cf, v124
	v_add_f32_e32 v112, v118, v112
	v_add_f32_e32 v113, v112, v113
	v_mul_f32_e64 v112, |v113|, s31
	v_exp_f32_e32 v112, v112
	v_fmac_f32_e32 v111, 0x3f317217, v124
	v_cmp_lt_f32_e64 s[62:63], |v124|, s20
	v_cndmask_b32_e32 v114, 0, v244, vcc
	v_add_f32_e32 v112, 1.0, v112
	v_cndmask_b32_e64 v111, v124, v111, s[62:63]
	v_cmp_gt_f32_e32 vcc, s34, v112
	v_sub_f32_e32 v111, v111, v114
	v_sub_f32_e32 v109, v109, v111
	v_cndmask_b32_e64 v114, 0, 32, vcc
	v_ldexp_f32 v112, v112, v114
	ds_read_b128 v[114:117], v88 offset:640
	ds_read_b128 v[118:121], v88 offset:656
	v_log_f32_e32 v126, v112
	v_fmamk_f32 v112, v109, 0x3d800000, v110
	v_min_f32_e32 v109, 0, v113
	s_waitcnt lgkmcnt(1)
	v_mov_b32_e32 v122, v114
	s_waitcnt lgkmcnt(0)
	v_mov_b32_e32 v123, v118
	v_mov_b32_e32 v118, v115
	v_pk_mul_f32 v[114:115], v[6:7], v[118:119]
	v_mov_b32_e32 v118, v116
	v_pk_fma_f32 v[114:115], v[4:5], v[122:123], v[114:115]
	v_mov_b32_e32 v119, v120
	v_pk_fma_f32 v[118:119], v[2:3], v[118:119], v[114:115]
	v_mov_b32_e32 v120, v117
	ds_read_b128 v[114:117], v88 offset:672
	ds_read_b128 v[122:125], v88 offset:688
	v_pk_fma_f32 v[118:119], v[0:1], v[120:121], v[118:119]
	v_mul_f32_e32 v111, 0x3f317217, v126
	v_add_f32_e32 v113, v65, v118
	v_add_f32_e32 v113, v113, v119
	s_waitcnt lgkmcnt(0)
	v_mov_b32_e32 v119, v122
	v_mov_b32_e32 v122, v115
	v_mov_b32_e32 v118, v114
	v_pk_mul_f32 v[114:115], v[78:79], v[122:123]
	v_fma_f32 v111, v126, s35, -v111
	v_pk_fma_f32 v[114:115], v[10:11], v[118:119], v[114:115]
	v_mov_b32_e32 v118, v116
	v_mov_b32_e32 v119, v124
	v_pk_fma_f32 v[114:115], v[8:9], v[118:119], v[114:115]
	v_mov_b32_e32 v124, v117
	v_pk_fma_f32 v[114:115], v[80:81], v[124:125], v[114:115]
	v_fmac_f32_e32 v111, 0x3377d1cf, v126
	v_add_f32_e32 v113, v113, v114
	v_add_f32_e32 v113, v113, v115
	v_mul_f32_e64 v114, |v113|, s31
	v_exp_f32_e32 v114, v114
	v_fmac_f32_e32 v111, 0x3f317217, v126
	v_cmp_lt_f32_e64 s[62:63], |v126|, s20
	v_cndmask_b32_e32 v115, 0, v244, vcc
	v_add_f32_e32 v114, 1.0, v114
	v_cndmask_b32_e64 v111, v126, v111, s[62:63]
	v_cmp_gt_f32_e32 vcc, s34, v114
	v_sub_f32_e32 v111, v111, v115
	v_sub_f32_e32 v109, v109, v111
	v_cndmask_b32_e64 v115, 0, 32, vcc
	v_ldexp_f32 v114, v114, v115
	v_log_f32_e32 v126, v114
	ds_read_b128 v[114:117], v88 offset:704
	ds_read_b128 v[118:121], v88 offset:720
	v_min_f32_e32 v111, 0, v113
	v_fmamk_f32 v109, v109, 0x3d800000, v112
	v_mul_f32_e32 v113, 0x3f317217, v126
	s_waitcnt lgkmcnt(1)
	v_mov_b32_e32 v122, v114
	s_waitcnt lgkmcnt(0)
	v_mov_b32_e32 v123, v118
	v_mov_b32_e32 v118, v115
	v_pk_mul_f32 v[114:115], v[6:7], v[118:119]
	v_mov_b32_e32 v118, v116
	v_pk_fma_f32 v[114:115], v[4:5], v[122:123], v[114:115]
	v_mov_b32_e32 v119, v120
	v_pk_fma_f32 v[118:119], v[2:3], v[118:119], v[114:115]
	v_mov_b32_e32 v120, v117
	ds_read_b128 v[114:117], v88 offset:736
	ds_read_b128 v[122:125], v88 offset:752
	v_pk_fma_f32 v[118:119], v[0:1], v[120:121], v[118:119]
	v_fma_f32 v113, v126, s35, -v113
	v_add_f32_e32 v118, v65, v118
	v_add_f32_e32 v120, v118, v119
	s_waitcnt lgkmcnt(0)
; #define LAS __attribute__((address_space(3)))
; __device__ __forceinline__ float log_sigmoid(float x) { return fminf(x, 0.f) - __logf(1.0f + __expf(-fabsf(x))); }
; __device__ __forceinline__ void gla_prep_item(Frame& F, const int jl, const int item) {
;     ...
;     float cum[32]; float run = 0.f;
; #pragma unroll
;     for (int t = 0; t < 32; ++t) { const LAS f32x4* g4 = (const LAS f32x4*)(glr + (half * 32 + t) * 16); float pre = bg;
; #pragma unroll
;         for (int r4 = 0; r4 < 4; ++r4) { const f32x4 g = g4[r4]; pre += g.x * wg[4 * r4] + g.y * wg[4 * r4 + 1] + g.z * wg[4 * r4 + 2] + g.w * wg[4 * r4 + 3]; }
;         run += log_sigmoid(pre) * 0.0625f; cum[t] = run; }
	v_mov_b32_e32 v119, v122
	v_mov_b32_e32 v122, v115
	v_mov_b32_e32 v118, v114
	v_pk_mul_f32 v[114:115], v[78:79], v[122:123]
	v_fmac_f32_e32 v113, 0x3377d1cf, v126
	v_pk_fma_f32 v[114:115], v[10:11], v[118:119], v[114:115]
	v_mov_b32_e32 v118, v116
	v_mov_b32_e32 v119, v124
	v_pk_fma_f32 v[114:115], v[8:9], v[118:119], v[114:115]
	v_mov_b32_e32 v124, v117
	v_pk_fma_f32 v[114:115], v[80:81], v[124:125], v[114:115]
	v_fmac_f32_e32 v113, 0x3f317217, v126
	v_add_f32_e32 v114, v120, v114
	v_add_f32_e32 v114, v114, v115
	v_mul_f32_e64 v115, |v114|, s31
	v_exp_f32_e32 v115, v115
	v_cmp_lt_f32_e64 s[62:63], |v126|, s20
	v_cndmask_b32_e32 v116, 0, v244, vcc
	v_add_f32_e32 v115, 1.0, v115
	v_cndmask_b32_e64 v113, v126, v113, s[62:63]
	v_cmp_gt_f32_e32 vcc, s34, v115
	v_sub_f32_e32 v113, v113, v116
	v_sub_f32_e32 v111, v111, v113
	v_cndmask_b32_e64 v116, 0, 32, vcc
	v_ldexp_f32 v115, v115, v116
	v_log_f32_e32 v126, v115
	v_min_f32_e32 v113, 0, v114
	ds_read_b128 v[114:117], v88 offset:768
	ds_read_b128 v[118:121], v88 offset:784
	v_fmamk_f32 v111, v111, 0x3d800000, v109
	v_mul_f32_e32 v122, 0x3f317217, v126
	v_fma_f32 v127, v126, s35, -v122
	s_waitcnt lgkmcnt(1)
	v_mov_b32_e32 v122, v114
	s_waitcnt lgkmcnt(0)
	v_mov_b32_e32 v123, v118
	v_mov_b32_e32 v118, v115
	v_pk_mul_f32 v[114:115], v[6:7], v[118:119]
	v_mov_b32_e32 v118, v116
	v_pk_fma_f32 v[114:115], v[4:5], v[122:123], v[114:115]
	v_mov_b32_e32 v119, v120
	v_pk_fma_f32 v[118:119], v[2:3], v[118:119], v[114:115]
	v_mov_b32_e32 v120, v117
	ds_read_b128 v[114:117], v88 offset:800
	ds_read_b128 v[122:125], v88 offset:816
	v_pk_fma_f32 v[118:119], v[0:1], v[120:121], v[118:119]
	v_fmac_f32_e32 v127, 0x3377d1cf, v126
	v_add_f32_e32 v118, v65, v118
	v_add_f32_e32 v120, v118, v119
	s_waitcnt lgkmcnt(0)
	v_mov_b32_e32 v119, v122
	v_mov_b32_e32 v122, v115
	v_mov_b32_e32 v118, v114
	v_pk_mul_f32 v[114:115], v[78:79], v[122:123]
	v_fmac_f32_e32 v127, 0x3f317217, v126
	v_pk_fma_f32 v[114:115], v[10:11], v[118:119], v[114:115]
	v_mov_b32_e32 v118, v116
	v_mov_b32_e32 v119, v124
	v_pk_fma_f32 v[114:115], v[8:9], v[118:119], v[114:115]
	v_mov_b32_e32 v124, v117
	v_pk_fma_f32 v[114:115], v[80:81], v[124:125], v[114:115]
	v_cmp_lt_f32_e64 s[62:63], |v126|, s20
	v_add_f32_e32 v114, v120, v114
	v_add_f32_e32 v114, v114, v115
	v_mul_f32_e64 v115, |v114|, s31
	v_exp_f32_e32 v115, v115
	v_cndmask_b32_e64 v116, v126, v127, s[62:63]
	v_cndmask_b32_e32 v117, 0, v244, vcc
	v_sub_f32_e32 v116, v116, v117
	v_add_f32_e32 v115, 1.0, v115
	v_cmp_gt_f32_e32 vcc, s34, v115
	v_sub_f32_e32 v113, v113, v116
	v_min_f32_e32 v127, 0, v114
	v_cndmask_b32_e64 v117, 0, 32, vcc
	v_ldexp_f32 v115, v115, v117
	v_log_f32_e32 v126, v115
	ds_read_b128 v[114:117], v88 offset:832
	ds_read_b128 v[118:121], v88 offset:848
	v_fmamk_f32 v113, v113, 0x3d800000, v111
	v_mul_f32_e32 v122, 0x3f317217, v126
	v_fma_f32 v128, v126, s35, -v122
	s_waitcnt lgkmcnt(0)
	v_mov_b32_e32 v123, v118
	v_mov_b32_e32 v118, v115
	v_mov_b32_e32 v122, v114
	v_pk_mul_f32 v[114:115], v[6:7], v[118:119]
	v_mov_b32_e32 v118, v116
	v_pk_fma_f32 v[114:115], v[4:5], v[122:123], v[114:115]
	v_mov_b32_e32 v119, v120
	v_pk_fma_f32 v[118:119], v[2:3], v[118:119], v[114:115]
	v_mov_b32_e32 v120, v117
	ds_read_b128 v[114:117], v88 offset:864
	ds_read_b128 v[122:125], v88 offset:880
	v_pk_fma_f32 v[118:119], v[0:1], v[120:121], v[118:119]
	v_fmac_f32_e32 v128, 0x3377d1cf, v126
	v_add_f32_e32 v118, v65, v118
	v_add_f32_e32 v120, v118, v119
	s_waitcnt lgkmcnt(0)
	v_mov_b32_e32 v119, v122
	v_mov_b32_e32 v122, v115
	v_mov_b32_e32 v118, v114
	v_pk_mul_f32 v[114:115], v[78:79], v[122:123]
	v_fmac_f32_e32 v128, 0x3f317217, v126
	v_pk_fma_f32 v[114:115], v[10:11], v[118:119], v[114:115]
	v_mov_b32_e32 v118, v116
	v_mov_b32_e32 v119, v124
	v_pk_fma_f32 v[114:115], v[8:9], v[118:119], v[114:115]
	v_mov_b32_e32 v124, v117
	v_pk_fma_f32 v[114:115], v[80:81], v[124:125], v[114:115]
	v_cmp_lt_f32_e64 s[62:63], |v126|, s20
	v_add_f32_e32 v114, v120, v114
	v_add_f32_e32 v115, v114, v115
	v_mul_f32_e64 v114, |v115|, s31
	v_exp_f32_e32 v114, v114
	v_cndmask_b32_e64 v116, v126, v128, s[62:63]
	v_cndmask_b32_e32 v117, 0, v244, vcc
	v_sub_f32_e32 v116, v116, v117
	v_add_f32_e32 v114, 1.0, v114
	v_cmp_gt_f32_e32 vcc, s34, v114
	v_min_f32_e32 v115, 0, v115
	s_nop 0
	v_cndmask_b32_e64 v117, 0, 32, vcc
	v_ldexp_f32 v114, v114, v117
	v_log_f32_e32 v128, v114
	v_sub_f32_e32 v114, v127, v116
	ds_read_b128 v[116:119], v88 offset:896
	ds_read_b128 v[120:123], v88 offset:912
	v_fmamk_f32 v114, v114, 0x3d800000, v113
	v_mul_f32_e32 v124, 0x3f317217, v128
	v_fma_f32 v129, v128, s35, -v124
	s_waitcnt lgkmcnt(1)
	v_mov_b32_e32 v124, v116
	s_waitcnt lgkmcnt(0)
	v_mov_b32_e32 v125, v120
	v_mov_b32_e32 v120, v117
	v_pk_mul_f32 v[116:117], v[6:7], v[120:121]
	v_mov_b32_e32 v120, v118
	v_pk_fma_f32 v[116:117], v[4:5], v[124:125], v[116:117]
	v_mov_b32_e32 v121, v122
	v_pk_fma_f32 v[120:121], v[2:3], v[120:121], v[116:117]
	v_mov_b32_e32 v122, v119
	ds_read_b128 v[116:119], v88 offset:928
	ds_read_b128 v[124:127], v88 offset:944
	v_pk_fma_f32 v[120:121], v[0:1], v[122:123], v[120:121]
	v_fmac_f32_e32 v129, 0x3377d1cf, v128
	v_add_f32_e32 v120, v65, v120
	v_add_f32_e32 v122, v120, v121
	s_waitcnt lgkmcnt(0)
; #define LAS __attribute__((address_space(3)))
; __device__ __forceinline__ float log_sigmoid(float x) { return fminf(x, 0.f) - __logf(1.0f + __expf(-fabsf(x))); }
; __device__ __forceinline__ void gla_prep_item(Frame& F, const int jl, const int item) {
;     ...
;     float cum[32]; float run = 0.f;
; #pragma unroll
;     for (int t = 0; t < 32; ++t) { const LAS f32x4* g4 = (const LAS f32x4*)(glr + (half * 32 + t) * 16); float pre = bg;
; #pragma unroll
;         for (int r4 = 0; r4 < 4; ++r4) { const f32x4 g = g4[r4]; pre += g.x * wg[4 * r4] + g.y * wg[4 * r4 + 1] + g.z * wg[4 * r4 + 2] + g.w * wg[4 * r4 + 3]; }
;         run += log_sigmoid(pre) * 0.0625f; cum[t] = run; }
	v_mov_b32_e32 v121, v124
	v_mov_b32_e32 v124, v117
	v_mov_b32_e32 v120, v116
	v_pk_mul_f32 v[116:117], v[78:79], v[124:125]
	v_fmac_f32_e32 v129, 0x3f317217, v128
	v_pk_fma_f32 v[116:117], v[10:11], v[120:121], v[116:117]
	v_mov_b32_e32 v120, v118
	v_mov_b32_e32 v121, v126
	v_pk_fma_f32 v[116:117], v[8:9], v[120:121], v[116:117]
	v_mov_b32_e32 v126, v119
	v_pk_fma_f32 v[116:117], v[80:81], v[126:127], v[116:117]
	v_cmp_lt_f32_e64 s[62:63], |v128|, s20
	v_add_f32_e32 v116, v122, v116
	v_add_f32_e32 v116, v116, v117
	v_mul_f32_e64 v117, |v116|, s31
	v_exp_f32_e32 v117, v117
	v_cndmask_b32_e64 v118, v128, v129, s[62:63]
	v_cndmask_b32_e32 v119, 0, v244, vcc
	v_sub_f32_e32 v118, v118, v119
	v_add_f32_e32 v117, 1.0, v117
	v_cmp_gt_f32_e32 vcc, s34, v117
	v_sub_f32_e32 v115, v115, v118
	v_min_f32_e32 v129, 0, v116
	v_cndmask_b32_e64 v119, 0, 32, vcc
	v_ldexp_f32 v117, v117, v119
	v_log_f32_e32 v128, v117
	ds_read_b128 v[116:119], v88 offset:960
	ds_read_b128 v[120:123], v88 offset:976
	v_fmamk_f32 v115, v115, 0x3d800000, v114
	v_mul_f32_e32 v124, 0x3f317217, v128
	v_fma_f32 v130, v128, s35, -v124
	s_waitcnt lgkmcnt(0)
	v_mov_b32_e32 v125, v120
	v_mov_b32_e32 v120, v117
	v_mov_b32_e32 v124, v116
	v_pk_mul_f32 v[116:117], v[6:7], v[120:121]
	v_mov_b32_e32 v120, v118
	v_pk_fma_f32 v[116:117], v[4:5], v[124:125], v[116:117]
	v_mov_b32_e32 v121, v122
	v_pk_fma_f32 v[120:121], v[2:3], v[120:121], v[116:117]
	v_mov_b32_e32 v122, v119
	ds_read_b128 v[116:119], v88 offset:992
	ds_read_b128 v[124:127], v88 offset:1008
	v_pk_fma_f32 v[120:121], v[0:1], v[122:123], v[120:121]
	v_fmac_f32_e32 v130, 0x3377d1cf, v128
	v_add_f32_e32 v120, v65, v120
	v_add_f32_e32 v122, v120, v121
	s_waitcnt lgkmcnt(0)
	v_mov_b32_e32 v121, v124
	v_mov_b32_e32 v124, v117
	v_mov_b32_e32 v120, v116
	v_pk_mul_f32 v[116:117], v[78:79], v[124:125]
	v_fmac_f32_e32 v130, 0x3f317217, v128
	v_pk_fma_f32 v[116:117], v[10:11], v[120:121], v[116:117]
	v_mov_b32_e32 v120, v118
	v_mov_b32_e32 v121, v126
	v_pk_fma_f32 v[116:117], v[8:9], v[120:121], v[116:117]
	v_mov_b32_e32 v126, v119
	v_pk_fma_f32 v[116:117], v[80:81], v[126:127], v[116:117]
	v_cmp_lt_f32_e64 s[62:63], |v128|, s20
	v_add_f32_e32 v116, v122, v116
	v_add_f32_e32 v117, v116, v117
	v_mul_f32_e64 v116, |v117|, s31
	v_exp_f32_e32 v116, v116
	v_cndmask_b32_e64 v118, v128, v130, s[62:63]
	v_cndmask_b32_e32 v119, 0, v244, vcc
	v_sub_f32_e32 v118, v118, v119
	v_add_f32_e32 v116, 1.0, v116
	v_cmp_gt_f32_e32 vcc, s34, v116
	v_min_f32_e32 v117, 0, v117
	s_nop 0
	v_cndmask_b32_e64 v119, 0, 32, vcc
	v_ldexp_f32 v116, v116, v119
	v_log_f32_e32 v130, v116
	v_sub_f32_e32 v116, v129, v118
	ds_read_b128 v[118:121], v88 offset:1024
	ds_read_b128 v[122:125], v88 offset:1040
	v_fmamk_f32 v116, v116, 0x3d800000, v115
	v_mul_f32_e32 v126, 0x3f317217, v130
	v_fma_f32 v131, v130, s35, -v126
	s_waitcnt lgkmcnt(1)
	v_mov_b32_e32 v126, v118
	s_waitcnt lgkmcnt(0)
	v_mov_b32_e32 v127, v122
	v_mov_b32_e32 v122, v119
	v_pk_mul_f32 v[118:119], v[6:7], v[122:123]
	v_mov_b32_e32 v122, v120
	v_pk_fma_f32 v[118:119], v[4:5], v[126:127], v[118:119]
	v_mov_b32_e32 v123, v124
	v_pk_fma_f32 v[122:123], v[2:3], v[122:123], v[118:119]
	v_mov_b32_e32 v124, v121
	ds_read_b128 v[118:121], v88 offset:1056
	ds_read_b128 v[126:129], v88 offset:1072
	v_pk_fma_f32 v[122:123], v[0:1], v[124:125], v[122:123]
	v_fmac_f32_e32 v131, 0x3377d1cf, v130
	v_add_f32_e32 v122, v65, v122
	v_add_f32_e32 v124, v122, v123
	s_waitcnt lgkmcnt(0)
	v_mov_b32_e32 v123, v126
	v_mov_b32_e32 v126, v119
	v_mov_b32_e32 v122, v118
	v_pk_mul_f32 v[118:119], v[78:79], v[126:127]
	v_fmac_f32_e32 v131, 0x3f317217, v130
	v_pk_fma_f32 v[118:119], v[10:11], v[122:123], v[118:119]
	v_mov_b32_e32 v122, v120
	v_mov_b32_e32 v123, v128
	v_pk_fma_f32 v[118:119], v[8:9], v[122:123], v[118:119]
	v_mov_b32_e32 v128, v121
	v_pk_fma_f32 v[118:119], v[80:81], v[128:129], v[118:119]
	v_cmp_lt_f32_e64 s[62:63], |v130|, s20
	v_add_f32_e32 v118, v124, v118
	v_add_f32_e32 v119, v118, v119
	v_mul_f32_e64 v118, |v119|, s31
	v_exp_f32_e32 v118, v118
	v_cndmask_b32_e64 v120, v130, v131, s[62:63]
	v_cndmask_b32_e32 v121, 0, v244, vcc
	v_sub_f32_e32 v120, v120, v121
	v_add_f32_e32 v118, 1.0, v118
	v_cmp_gt_f32_e32 vcc, s34, v118
	v_sub_f32_e32 v117, v117, v120
	s_nop 0
	v_cndmask_b32_e64 v121, 0, 32, vcc
	v_ldexp_f32 v118, v118, v121
	ds_read_b128 v[120:123], v88 offset:1088
	ds_read_b128 v[124:127], v88 offset:1104
	v_log_f32_e32 v132, v118
	v_fmamk_f32 v118, v117, 0x3d800000, v116
	v_min_f32_e32 v117, 0, v119
	s_waitcnt lgkmcnt(1)
	v_mov_b32_e32 v128, v120
	s_waitcnt lgkmcnt(0)
	v_mov_b32_e32 v129, v124
	v_mov_b32_e32 v124, v121
	v_pk_mul_f32 v[120:121], v[6:7], v[124:125]
	v_mov_b32_e32 v124, v122
	v_pk_fma_f32 v[120:121], v[4:5], v[128:129], v[120:121]
	v_mov_b32_e32 v125, v126
	v_pk_fma_f32 v[124:125], v[2:3], v[124:125], v[120:121]
	v_mov_b32_e32 v126, v123
	ds_read_b128 v[120:123], v88 offset:1120
	ds_read_b128 v[128:131], v88 offset:1136
	v_pk_fma_f32 v[124:125], v[0:1], v[126:127], v[124:125]
	v_mul_f32_e32 v119, 0x3f317217, v132
	v_add_f32_e32 v124, v65, v124
	v_add_f32_e32 v126, v124, v125
	s_waitcnt lgkmcnt(0)
; #define LAS __attribute__((address_space(3)))
; __device__ __forceinline__ float log_sigmoid(float x) { return fminf(x, 0.f) - __logf(1.0f + __expf(-fabsf(x))); }
; __device__ __forceinline__ void gla_prep_item(Frame& F, const int jl, const int item) {
;     ...
;     float cum[32]; float run = 0.f;
; #pragma unroll
;     for (int t = 0; t < 32; ++t) { const LAS f32x4* g4 = (const LAS f32x4*)(glr + (half * 32 + t) * 16); float pre = bg;
; #pragma unroll
;         for (int r4 = 0; r4 < 4; ++r4) { const f32x4 g = g4[r4]; pre += g.x * wg[4 * r4] + g.y * wg[4 * r4 + 1] + g.z * wg[4 * r4 + 2] + g.w * wg[4 * r4 + 3]; }
;         run += log_sigmoid(pre) * 0.0625f; cum[t] = run; }
	v_mov_b32_e32 v125, v128
	v_mov_b32_e32 v128, v121
	v_mov_b32_e32 v124, v120
	v_pk_mul_f32 v[120:121], v[78:79], v[128:129]
	v_fma_f32 v119, v132, s35, -v119
	v_pk_fma_f32 v[120:121], v[10:11], v[124:125], v[120:121]
	v_mov_b32_e32 v124, v122
	v_mov_b32_e32 v125, v130
	v_pk_fma_f32 v[120:121], v[8:9], v[124:125], v[120:121]
	v_mov_b32_e32 v130, v123
	v_pk_fma_f32 v[120:121], v[80:81], v[130:131], v[120:121]
	v_fmac_f32_e32 v119, 0x3377d1cf, v132
	v_add_f32_e32 v120, v126, v120
	v_add_f32_e32 v121, v120, v121
	v_mul_f32_e64 v120, |v121|, s31
	v_exp_f32_e32 v120, v120
	v_fmac_f32_e32 v119, 0x3f317217, v132
	v_cmp_lt_f32_e64 s[62:63], |v132|, s20
	v_cndmask_b32_e32 v122, 0, v244, vcc
	v_add_f32_e32 v120, 1.0, v120
	v_cndmask_b32_e64 v119, v132, v119, s[62:63]
	v_cmp_gt_f32_e32 vcc, s34, v120
	v_sub_f32_e32 v119, v119, v122
	v_sub_f32_e32 v117, v117, v119
	v_cndmask_b32_e64 v122, 0, 32, vcc
	v_ldexp_f32 v120, v120, v122
	ds_read_b128 v[122:125], v88 offset:1152
	ds_read_b128 v[126:129], v88 offset:1168
	v_log_f32_e32 v134, v120
	v_fmamk_f32 v120, v117, 0x3d800000, v118
	v_min_f32_e32 v117, 0, v121
	s_waitcnt lgkmcnt(1)
	v_mov_b32_e32 v130, v122
	s_waitcnt lgkmcnt(0)
	v_mov_b32_e32 v131, v126
	v_mov_b32_e32 v126, v123
	v_pk_mul_f32 v[122:123], v[6:7], v[126:127]
	v_mov_b32_e32 v126, v124
	v_pk_fma_f32 v[122:123], v[4:5], v[130:131], v[122:123]
	v_mov_b32_e32 v127, v128
	v_pk_fma_f32 v[126:127], v[2:3], v[126:127], v[122:123]
	v_mov_b32_e32 v128, v125
	ds_read_b128 v[122:125], v88 offset:1184
	ds_read_b128 v[130:133], v88 offset:1200
	v_pk_fma_f32 v[126:127], v[0:1], v[128:129], v[126:127]
	v_mul_f32_e32 v119, 0x3f317217, v134
	v_add_f32_e32 v121, v65, v126
	v_add_f32_e32 v121, v121, v127
	s_waitcnt lgkmcnt(0)
	v_mov_b32_e32 v127, v130
	v_mov_b32_e32 v130, v123
	v_mov_b32_e32 v126, v122
	v_pk_mul_f32 v[122:123], v[78:79], v[130:131]
	v_fma_f32 v119, v134, s35, -v119
	v_pk_fma_f32 v[122:123], v[10:11], v[126:127], v[122:123]
	v_mov_b32_e32 v126, v124
	v_mov_b32_e32 v127, v132
	v_pk_fma_f32 v[122:123], v[8:9], v[126:127], v[122:123]
	v_mov_b32_e32 v132, v125
	v_pk_fma_f32 v[122:123], v[80:81], v[132:133], v[122:123]
	v_fmac_f32_e32 v119, 0x3377d1cf, v134
	v_add_f32_e32 v121, v121, v122
	v_add_f32_e32 v121, v121, v123
	v_mul_f32_e64 v122, |v121|, s31
	v_exp_f32_e32 v122, v122
	v_fmac_f32_e32 v119, 0x3f317217, v134
	v_cmp_lt_f32_e64 s[62:63], |v134|, s20
	v_cndmask_b32_e32 v123, 0, v244, vcc
	v_add_f32_e32 v122, 1.0, v122
	v_cndmask_b32_e64 v119, v134, v119, s[62:63]
	v_cmp_gt_f32_e32 vcc, s34, v122
	v_sub_f32_e32 v119, v119, v123
	v_sub_f32_e32 v117, v117, v119
	v_cndmask_b32_e64 v123, 0, 32, vcc
	v_ldexp_f32 v122, v122, v123
	v_log_f32_e32 v134, v122
	ds_read_b128 v[122:125], v88 offset:1216
	ds_read_b128 v[126:129], v88 offset:1232
	v_min_f32_e32 v119, 0, v121
	v_fmamk_f32 v117, v117, 0x3d800000, v120
	v_mul_f32_e32 v121, 0x3f317217, v134
	s_waitcnt lgkmcnt(1)
	v_mov_b32_e32 v130, v122
	s_waitcnt lgkmcnt(0)
	v_mov_b32_e32 v131, v126
	v_mov_b32_e32 v126, v123
	v_pk_mul_f32 v[122:123], v[6:7], v[126:127]
	v_mov_b32_e32 v126, v124
	v_pk_fma_f32 v[122:123], v[4:5], v[130:131], v[122:123]
	v_mov_b32_e32 v127, v128
	v_pk_fma_f32 v[126:127], v[2:3], v[126:127], v[122:123]
	v_mov_b32_e32 v128, v125
	ds_read_b128 v[122:125], v88 offset:1248
	ds_read_b128 v[130:133], v88 offset:1264
	v_pk_fma_f32 v[126:127], v[0:1], v[128:129], v[126:127]
	v_fma_f32 v121, v134, s35, -v121
	v_add_f32_e32 v126, v65, v126
	v_add_f32_e32 v128, v126, v127
	s_waitcnt lgkmcnt(0)
	v_mov_b32_e32 v127, v130
	v_mov_b32_e32 v130, v123
	v_mov_b32_e32 v126, v122
	v_pk_mul_f32 v[122:123], v[78:79], v[130:131]
	v_fmac_f32_e32 v121, 0x3377d1cf, v134
	v_pk_fma_f32 v[122:123], v[10:11], v[126:127], v[122:123]
	v_mov_b32_e32 v126, v124
	v_mov_b32_e32 v127, v132
	v_pk_fma_f32 v[122:123], v[8:9], v[126:127], v[122:123]
	v_mov_b32_e32 v132, v125
	v_pk_fma_f32 v[122:123], v[80:81], v[132:133], v[122:123]
	v_fmac_f32_e32 v121, 0x3f317217, v134
	v_add_f32_e32 v122, v128, v122
	v_add_f32_e32 v122, v122, v123
	v_mul_f32_e64 v123, |v122|, s31
	v_exp_f32_e32 v123, v123
	v_cmp_lt_f32_e64 s[62:63], |v134|, s20
	v_cndmask_b32_e32 v124, 0, v244, vcc
	v_add_f32_e32 v123, 1.0, v123
	v_cndmask_b32_e64 v121, v134, v121, s[62:63]
	v_cmp_gt_f32_e32 vcc, s34, v123
	v_sub_f32_e32 v121, v121, v124
	v_sub_f32_e32 v119, v119, v121
	v_cndmask_b32_e64 v124, 0, 32, vcc
	v_ldexp_f32 v123, v123, v124
	v_log_f32_e32 v134, v123
	v_min_f32_e32 v121, 0, v122
	ds_read_b128 v[122:125], v88 offset:1280
	ds_read_b128 v[126:129], v88 offset:1296
	v_fmamk_f32 v119, v119, 0x3d800000, v117
	v_mul_f32_e32 v130, 0x3f317217, v134
	v_fma_f32 v135, v134, s35, -v130
	s_waitcnt lgkmcnt(1)
	v_mov_b32_e32 v130, v122
	s_waitcnt lgkmcnt(0)
	v_mov_b32_e32 v131, v126
	v_mov_b32_e32 v126, v123
	v_pk_mul_f32 v[122:123], v[6:7], v[126:127]
	v_mov_b32_e32 v126, v124
	v_pk_fma_f32 v[122:123], v[4:5], v[130:131], v[122:123]
	v_mov_b32_e32 v127, v128
	v_pk_fma_f32 v[126:127], v[2:3], v[126:127], v[122:123]
	v_mov_b32_e32 v128, v125
	ds_read_b128 v[122:125], v88 offset:1312
	ds_read_b128 v[130:133], v88 offset:1328
	v_pk_fma_f32 v[126:127], v[0:1], v[128:129], v[126:127]
	v_fmac_f32_e32 v135, 0x3377d1cf, v134
	v_add_f32_e32 v126, v65, v126
	v_add_f32_e32 v128, v126, v127
	s_waitcnt lgkmcnt(0)
; #define LAS __attribute__((address_space(3)))
; __device__ __forceinline__ float log_sigmoid(float x) { return fminf(x, 0.f) - __logf(1.0f + __expf(-fabsf(x))); }
; __device__ __forceinline__ void gla_prep_item(Frame& F, const int jl, const int item) {
;     ...
;     float cum[32]; float run = 0.f;
; #pragma unroll
;     for (int t = 0; t < 32; ++t) { const LAS f32x4* g4 = (const LAS f32x4*)(glr + (half * 32 + t) * 16); float pre = bg;
; #pragma unroll
;         for (int r4 = 0; r4 < 4; ++r4) { const f32x4 g = g4[r4]; pre += g.x * wg[4 * r4] + g.y * wg[4 * r4 + 1] + g.z * wg[4 * r4 + 2] + g.w * wg[4 * r4 + 3]; }
;         run += log_sigmoid(pre) * 0.0625f; cum[t] = run; }
	v_mov_b32_e32 v127, v130
	v_mov_b32_e32 v130, v123
	v_mov_b32_e32 v126, v122
	v_pk_mul_f32 v[122:123], v[78:79], v[130:131]
	v_fmac_f32_e32 v135, 0x3f317217, v134
	v_pk_fma_f32 v[122:123], v[10:11], v[126:127], v[122:123]
	v_mov_b32_e32 v126, v124
	v_mov_b32_e32 v127, v132
	v_pk_fma_f32 v[122:123], v[8:9], v[126:127], v[122:123]
	v_mov_b32_e32 v132, v125
	v_pk_fma_f32 v[122:123], v[80:81], v[132:133], v[122:123]
	v_cmp_lt_f32_e64 s[62:63], |v134|, s20
	v_add_f32_e32 v122, v128, v122
	v_add_f32_e32 v122, v122, v123
	v_mul_f32_e64 v123, |v122|, s31
	v_exp_f32_e32 v123, v123
	v_cndmask_b32_e64 v124, v134, v135, s[62:63]
	v_cndmask_b32_e32 v125, 0, v244, vcc
	v_sub_f32_e32 v124, v124, v125
	v_add_f32_e32 v123, 1.0, v123
	v_cmp_gt_f32_e32 vcc, s34, v123
	v_sub_f32_e32 v121, v121, v124
	v_min_f32_e32 v135, 0, v122
	v_cndmask_b32_e64 v125, 0, 32, vcc
	v_ldexp_f32 v123, v123, v125
	v_log_f32_e32 v134, v123
	ds_read_b128 v[122:125], v88 offset:1344
	ds_read_b128 v[126:129], v88 offset:1360
	v_fmamk_f32 v121, v121, 0x3d800000, v119
	v_mul_f32_e32 v130, 0x3f317217, v134
	v_fma_f32 v136, v134, s35, -v130
	s_waitcnt lgkmcnt(0)
	v_mov_b32_e32 v131, v126
	v_mov_b32_e32 v126, v123
	v_mov_b32_e32 v130, v122
	v_pk_mul_f32 v[122:123], v[6:7], v[126:127]
	v_mov_b32_e32 v126, v124
	v_pk_fma_f32 v[122:123], v[4:5], v[130:131], v[122:123]
	v_mov_b32_e32 v127, v128
	v_pk_fma_f32 v[126:127], v[2:3], v[126:127], v[122:123]
	v_mov_b32_e32 v128, v125
	ds_read_b128 v[122:125], v88 offset:1376
	ds_read_b128 v[130:133], v88 offset:1392
	v_pk_fma_f32 v[126:127], v[0:1], v[128:129], v[126:127]
	v_fmac_f32_e32 v136, 0x3377d1cf, v134
	v_add_f32_e32 v126, v65, v126
	v_add_f32_e32 v128, v126, v127
	s_waitcnt lgkmcnt(0)
	v_mov_b32_e32 v127, v130
	v_mov_b32_e32 v130, v123
	v_mov_b32_e32 v126, v122
	v_pk_mul_f32 v[122:123], v[78:79], v[130:131]
	v_fmac_f32_e32 v136, 0x3f317217, v134
	v_pk_fma_f32 v[122:123], v[10:11], v[126:127], v[122:123]
	v_mov_b32_e32 v126, v124
	v_mov_b32_e32 v127, v132
	v_pk_fma_f32 v[122:123], v[8:9], v[126:127], v[122:123]
	v_mov_b32_e32 v132, v125
	v_pk_fma_f32 v[122:123], v[80:81], v[132:133], v[122:123]
	v_cmp_lt_f32_e64 s[62:63], |v134|, s20
	v_add_f32_e32 v122, v128, v122
	v_add_f32_e32 v123, v122, v123
	v_mul_f32_e64 v122, |v123|, s31
	v_exp_f32_e32 v122, v122
	v_cndmask_b32_e64 v124, v134, v136, s[62:63]
	v_cndmask_b32_e32 v125, 0, v244, vcc
	v_sub_f32_e32 v124, v124, v125
	v_add_f32_e32 v122, 1.0, v122
	v_cmp_gt_f32_e32 vcc, s34, v122
	v_min_f32_e32 v123, 0, v123
	s_nop 0
	v_cndmask_b32_e64 v125, 0, 32, vcc
	v_ldexp_f32 v122, v122, v125
	v_log_f32_e32 v136, v122
	v_sub_f32_e32 v122, v135, v124
	ds_read_b128 v[124:127], v88 offset:1408
	ds_read_b128 v[128:131], v88 offset:1424
	v_fmamk_f32 v122, v122, 0x3d800000, v121
	v_mul_f32_e32 v132, 0x3f317217, v136
	v_fma_f32 v137, v136, s35, -v132
	s_waitcnt lgkmcnt(1)
	v_mov_b32_e32 v132, v124
	s_waitcnt lgkmcnt(0)
	v_mov_b32_e32 v133, v128
	v_mov_b32_e32 v128, v125
	v_pk_mul_f32 v[124:125], v[6:7], v[128:129]
	v_mov_b32_e32 v128, v126
	v_pk_fma_f32 v[124:125], v[4:5], v[132:133], v[124:125]
	v_mov_b32_e32 v129, v130
	v_pk_fma_f32 v[128:129], v[2:3], v[128:129], v[124:125]
	v_mov_b32_e32 v130, v127
	ds_read_b128 v[124:127], v88 offset:1440
	ds_read_b128 v[132:135], v88 offset:1456
	v_pk_fma_f32 v[128:129], v[0:1], v[130:131], v[128:129]
	v_fmac_f32_e32 v137, 0x3377d1cf, v136
	v_add_f32_e32 v128, v65, v128
	v_add_f32_e32 v130, v128, v129
	s_waitcnt lgkmcnt(0)
	v_mov_b32_e32 v129, v132
	v_mov_b32_e32 v132, v125
	v_mov_b32_e32 v128, v124
	v_pk_mul_f32 v[124:125], v[78:79], v[132:133]
	v_fmac_f32_e32 v137, 0x3f317217, v136
	v_pk_fma_f32 v[124:125], v[10:11], v[128:129], v[124:125]
	v_mov_b32_e32 v128, v126
	v_mov_b32_e32 v129, v134
	v_pk_fma_f32 v[124:125], v[8:9], v[128:129], v[124:125]
	v_mov_b32_e32 v134, v127
	v_pk_fma_f32 v[124:125], v[80:81], v[134:135], v[124:125]
	v_cmp_lt_f32_e64 s[62:63], |v136|, s20
	v_add_f32_e32 v124, v130, v124
	v_add_f32_e32 v124, v124, v125
	v_mul_f32_e64 v125, |v124|, s31
	v_exp_f32_e32 v125, v125
	v_cndmask_b32_e64 v126, v136, v137, s[62:63]
	v_cndmask_b32_e32 v127, 0, v244, vcc
	v_sub_f32_e32 v126, v126, v127
	v_add_f32_e32 v125, 1.0, v125
	v_cmp_gt_f32_e32 vcc, s34, v125
	v_sub_f32_e32 v123, v123, v126
	v_min_f32_e32 v137, 0, v124
	v_cndmask_b32_e64 v127, 0, 32, vcc
	v_ldexp_f32 v125, v125, v127
	v_log_f32_e32 v136, v125
	ds_read_b128 v[124:127], v88 offset:1472
	ds_read_b128 v[128:131], v88 offset:1488
	v_fmamk_f32 v123, v123, 0x3d800000, v122
	v_mul_f32_e32 v132, 0x3f317217, v136
	v_fma_f32 v138, v136, s35, -v132
	s_waitcnt lgkmcnt(0)
	v_mov_b32_e32 v133, v128
	v_mov_b32_e32 v128, v125
	v_mov_b32_e32 v132, v124
	v_pk_mul_f32 v[124:125], v[6:7], v[128:129]
	v_mov_b32_e32 v128, v126
	v_pk_fma_f32 v[124:125], v[4:5], v[132:133], v[124:125]
	v_mov_b32_e32 v129, v130
	v_pk_fma_f32 v[128:129], v[2:3], v[128:129], v[124:125]
	v_mov_b32_e32 v130, v127
	ds_read_b128 v[124:127], v88 offset:1504
	ds_read_b128 v[132:135], v88 offset:1520
	v_pk_fma_f32 v[128:129], v[0:1], v[130:131], v[128:129]
	v_fmac_f32_e32 v138, 0x3377d1cf, v136
	v_add_f32_e32 v128, v65, v128
	v_add_f32_e32 v130, v128, v129
	s_waitcnt lgkmcnt(0)
; #define LAS __attribute__((address_space(3)))
; __device__ __forceinline__ float log_sigmoid(float x) { return fminf(x, 0.f) - __logf(1.0f + __expf(-fabsf(x))); }
; __device__ __forceinline__ void gla_prep_item(Frame& F, const int jl, const int item) {
;     ...
;     float cum[32]; float run = 0.f;
; #pragma unroll
;     for (int t = 0; t < 32; ++t) { const LAS f32x4* g4 = (const LAS f32x4*)(glr + (half * 32 + t) * 16); float pre = bg;
; #pragma unroll
;         for (int r4 = 0; r4 < 4; ++r4) { const f32x4 g = g4[r4]; pre += g.x * wg[4 * r4] + g.y * wg[4 * r4 + 1] + g.z * wg[4 * r4 + 2] + g.w * wg[4 * r4 + 3]; }
;         run += log_sigmoid(pre) * 0.0625f; cum[t] = run; }
	v_mov_b32_e32 v129, v132
	v_mov_b32_e32 v132, v125
	v_mov_b32_e32 v128, v124
	v_pk_mul_f32 v[124:125], v[78:79], v[132:133]
	v_fmac_f32_e32 v138, 0x3f317217, v136
	v_pk_fma_f32 v[124:125], v[10:11], v[128:129], v[124:125]
	v_mov_b32_e32 v128, v126
	v_mov_b32_e32 v129, v134
	v_pk_fma_f32 v[124:125], v[8:9], v[128:129], v[124:125]
	v_mov_b32_e32 v134, v127
	v_pk_fma_f32 v[124:125], v[80:81], v[134:135], v[124:125]
	v_cmp_lt_f32_e64 s[62:63], |v136|, s20
	v_add_f32_e32 v124, v130, v124
	v_add_f32_e32 v125, v124, v125
	v_mul_f32_e64 v124, |v125|, s31
	v_exp_f32_e32 v124, v124
	v_cndmask_b32_e64 v126, v136, v138, s[62:63]
	v_cndmask_b32_e32 v127, 0, v244, vcc
	v_sub_f32_e32 v126, v126, v127
	v_add_f32_e32 v124, 1.0, v124
	v_cmp_gt_f32_e32 vcc, s34, v124
	v_min_f32_e32 v125, 0, v125
	s_nop 0
	v_cndmask_b32_e64 v127, 0, 32, vcc
	v_ldexp_f32 v124, v124, v127
	v_log_f32_e32 v138, v124
	v_sub_f32_e32 v124, v137, v126
	ds_read_b128 v[126:129], v88 offset:1536
	ds_read_b128 v[130:133], v88 offset:1552
	v_fmamk_f32 v124, v124, 0x3d800000, v123
	v_mul_f32_e32 v134, 0x3f317217, v138
	v_fma_f32 v139, v138, s35, -v134
	s_waitcnt lgkmcnt(1)
	v_mov_b32_e32 v134, v126
	s_waitcnt lgkmcnt(0)
	v_mov_b32_e32 v135, v130
	v_mov_b32_e32 v130, v127
	v_pk_mul_f32 v[126:127], v[6:7], v[130:131]
	v_mov_b32_e32 v130, v128
	v_pk_fma_f32 v[126:127], v[4:5], v[134:135], v[126:127]
	v_mov_b32_e32 v131, v132
	v_pk_fma_f32 v[130:131], v[2:3], v[130:131], v[126:127]
	v_mov_b32_e32 v132, v129
	ds_read_b128 v[126:129], v88 offset:1568
	ds_read_b128 v[134:137], v88 offset:1584
	v_pk_fma_f32 v[130:131], v[0:1], v[132:133], v[130:131]
	v_fmac_f32_e32 v139, 0x3377d1cf, v138
	v_add_f32_e32 v130, v65, v130
	v_add_f32_e32 v132, v130, v131
	s_waitcnt lgkmcnt(0)
	v_mov_b32_e32 v131, v134
	v_mov_b32_e32 v134, v127
	v_mov_b32_e32 v130, v126
	v_pk_mul_f32 v[126:127], v[78:79], v[134:135]
	v_fmac_f32_e32 v139, 0x3f317217, v138
	v_pk_fma_f32 v[126:127], v[10:11], v[130:131], v[126:127]
	v_mov_b32_e32 v130, v128
	v_mov_b32_e32 v131, v136
	v_pk_fma_f32 v[126:127], v[8:9], v[130:131], v[126:127]
	v_mov_b32_e32 v136, v129
	v_pk_fma_f32 v[126:127], v[80:81], v[136:137], v[126:127]
	v_cmp_lt_f32_e64 s[62:63], |v138|, s20
	v_add_f32_e32 v126, v132, v126
	v_add_f32_e32 v127, v126, v127
	v_mul_f32_e64 v126, |v127|, s31
	v_exp_f32_e32 v126, v126
	v_cndmask_b32_e64 v128, v138, v139, s[62:63]
	v_cndmask_b32_e32 v129, 0, v244, vcc
	v_sub_f32_e32 v128, v128, v129
	v_add_f32_e32 v126, 1.0, v126
	v_cmp_gt_f32_e32 vcc, s34, v126
	v_sub_f32_e32 v125, v125, v128
	s_nop 0
	v_cndmask_b32_e64 v129, 0, 32, vcc
	v_ldexp_f32 v126, v126, v129
	ds_read_b128 v[128:131], v88 offset:1600
	ds_read_b128 v[132:135], v88 offset:1616
	v_log_f32_e32 v140, v126
	v_fmamk_f32 v126, v125, 0x3d800000, v124
	v_min_f32_e32 v125, 0, v127
	s_waitcnt lgkmcnt(1)
	v_mov_b32_e32 v136, v128
	s_waitcnt lgkmcnt(0)
	v_mov_b32_e32 v137, v132
	v_mov_b32_e32 v132, v129
	v_pk_mul_f32 v[128:129], v[6:7], v[132:133]
	v_mov_b32_e32 v132, v130
	v_pk_fma_f32 v[128:129], v[4:5], v[136:137], v[128:129]
	v_mov_b32_e32 v133, v134
	v_pk_fma_f32 v[132:133], v[2:3], v[132:133], v[128:129]
	v_mov_b32_e32 v134, v131
	ds_read_b128 v[128:131], v88 offset:1632
	ds_read_b128 v[136:139], v88 offset:1648
	v_pk_fma_f32 v[132:133], v[0:1], v[134:135], v[132:133]
	v_mul_f32_e32 v127, 0x3f317217, v140
	v_add_f32_e32 v132, v65, v132
	v_add_f32_e32 v134, v132, v133
	s_waitcnt lgkmcnt(0)
	v_mov_b32_e32 v133, v136
	v_mov_b32_e32 v136, v129
	v_mov_b32_e32 v132, v128
	v_pk_mul_f32 v[128:129], v[78:79], v[136:137]
	v_fma_f32 v127, v140, s35, -v127
	v_pk_fma_f32 v[128:129], v[10:11], v[132:133], v[128:129]
	v_mov_b32_e32 v132, v130
	v_mov_b32_e32 v133, v138
	v_pk_fma_f32 v[128:129], v[8:9], v[132:133], v[128:129]
	v_mov_b32_e32 v138, v131
	v_pk_fma_f32 v[128:129], v[80:81], v[138:139], v[128:129]
	v_fmac_f32_e32 v127, 0x3377d1cf, v140
	v_add_f32_e32 v128, v134, v128
	v_add_f32_e32 v129, v128, v129
	v_mul_f32_e64 v128, |v129|, s31
	v_exp_f32_e32 v128, v128
	v_fmac_f32_e32 v127, 0x3f317217, v140
	v_cmp_lt_f32_e64 s[62:63], |v140|, s20
	v_cndmask_b32_e32 v130, 0, v244, vcc
	v_add_f32_e32 v128, 1.0, v128
	v_cndmask_b32_e64 v127, v140, v127, s[62:63]
	v_cmp_gt_f32_e32 vcc, s34, v128
	v_sub_f32_e32 v127, v127, v130
	v_sub_f32_e32 v125, v125, v127
	v_cndmask_b32_e64 v130, 0, 32, vcc
	v_ldexp_f32 v128, v128, v130
	ds_read_b128 v[130:133], v88 offset:1664
	ds_read_b128 v[134:137], v88 offset:1680
	v_log_f32_e32 v142, v128
	v_fmamk_f32 v128, v125, 0x3d800000, v126
	v_min_f32_e32 v125, 0, v129
	s_waitcnt lgkmcnt(1)
	v_mov_b32_e32 v138, v130
	s_waitcnt lgkmcnt(0)
	v_mov_b32_e32 v139, v134
	v_mov_b32_e32 v134, v131
	v_pk_mul_f32 v[130:131], v[6:7], v[134:135]
	v_mov_b32_e32 v134, v132
	v_pk_fma_f32 v[130:131], v[4:5], v[138:139], v[130:131]
	v_mov_b32_e32 v135, v136
	v_pk_fma_f32 v[134:135], v[2:3], v[134:135], v[130:131]
	v_mov_b32_e32 v136, v133
	ds_read_b128 v[130:133], v88 offset:1696
	ds_read_b128 v[138:141], v88 offset:1712
	v_pk_fma_f32 v[134:135], v[0:1], v[136:137], v[134:135]
	v_mul_f32_e32 v127, 0x3f317217, v142
	v_add_f32_e32 v129, v65, v134
	v_add_f32_e32 v129, v129, v135
	s_waitcnt lgkmcnt(0)
; #define LAS __attribute__((address_space(3)))
; __device__ __forceinline__ float log_sigmoid(float x) { return fminf(x, 0.f) - __logf(1.0f + __expf(-fabsf(x))); }
; __device__ __forceinline__ void gla_prep_item(Frame& F, const int jl, const int item) {
;     ...
;     float cum[32]; float run = 0.f;
; #pragma unroll
;     for (int t = 0; t < 32; ++t) { const LAS f32x4* g4 = (const LAS f32x4*)(glr + (half * 32 + t) * 16); float pre = bg;
; #pragma unroll
;         for (int r4 = 0; r4 < 4; ++r4) { const f32x4 g = g4[r4]; pre += g.x * wg[4 * r4] + g.y * wg[4 * r4 + 1] + g.z * wg[4 * r4 + 2] + g.w * wg[4 * r4 + 3]; }
;         run += log_sigmoid(pre) * 0.0625f; cum[t] = run; }
	v_mov_b32_e32 v135, v138
	v_mov_b32_e32 v138, v131
	v_mov_b32_e32 v134, v130
	v_pk_mul_f32 v[130:131], v[78:79], v[138:139]
	v_fma_f32 v127, v142, s35, -v127
	v_pk_fma_f32 v[130:131], v[10:11], v[134:135], v[130:131]
	v_mov_b32_e32 v134, v132
	v_mov_b32_e32 v135, v140
	v_pk_fma_f32 v[130:131], v[8:9], v[134:135], v[130:131]
	v_mov_b32_e32 v140, v133
	v_pk_fma_f32 v[130:131], v[80:81], v[140:141], v[130:131]
	v_fmac_f32_e32 v127, 0x3377d1cf, v142
	v_add_f32_e32 v129, v129, v130
	v_add_f32_e32 v129, v129, v131
	v_mul_f32_e64 v130, |v129|, s31
	v_exp_f32_e32 v130, v130
	v_fmac_f32_e32 v127, 0x3f317217, v142
	v_cmp_lt_f32_e64 s[62:63], |v142|, s20
	v_cndmask_b32_e32 v131, 0, v244, vcc
	v_add_f32_e32 v130, 1.0, v130
	v_cndmask_b32_e64 v127, v142, v127, s[62:63]
	v_cmp_gt_f32_e32 vcc, s34, v130
	v_sub_f32_e32 v127, v127, v131
	v_sub_f32_e32 v125, v125, v127
	v_cndmask_b32_e64 v131, 0, 32, vcc
	v_ldexp_f32 v130, v130, v131
	v_log_f32_e32 v142, v130
	ds_read_b128 v[130:133], v88 offset:1728
	ds_read_b128 v[134:137], v88 offset:1744
	v_min_f32_e32 v127, 0, v129
	v_fmamk_f32 v125, v125, 0x3d800000, v128
	v_mul_f32_e32 v129, 0x3f317217, v142
	s_waitcnt lgkmcnt(1)
	v_mov_b32_e32 v138, v130
	s_waitcnt lgkmcnt(0)
	v_mov_b32_e32 v139, v134
	v_mov_b32_e32 v134, v131
	v_pk_mul_f32 v[130:131], v[6:7], v[134:135]
	v_mov_b32_e32 v134, v132
	v_pk_fma_f32 v[130:131], v[4:5], v[138:139], v[130:131]
	v_mov_b32_e32 v135, v136
	v_pk_fma_f32 v[134:135], v[2:3], v[134:135], v[130:131]
	v_mov_b32_e32 v136, v133
	ds_read_b128 v[130:133], v88 offset:1760
	ds_read_b128 v[138:141], v88 offset:1776
	v_pk_fma_f32 v[134:135], v[0:1], v[136:137], v[134:135]
	v_fma_f32 v129, v142, s35, -v129
	v_add_f32_e32 v134, v65, v134
	v_add_f32_e32 v136, v134, v135
	s_waitcnt lgkmcnt(0)
	v_mov_b32_e32 v135, v138
	v_mov_b32_e32 v138, v131
	v_mov_b32_e32 v134, v130
	v_pk_mul_f32 v[130:131], v[78:79], v[138:139]
	v_fmac_f32_e32 v129, 0x3377d1cf, v142
	v_pk_fma_f32 v[130:131], v[10:11], v[134:135], v[130:131]
	v_mov_b32_e32 v134, v132
	v_mov_b32_e32 v135, v140
	v_pk_fma_f32 v[130:131], v[8:9], v[134:135], v[130:131]
	v_mov_b32_e32 v140, v133
	v_pk_fma_f32 v[130:131], v[80:81], v[140:141], v[130:131]
	v_fmac_f32_e32 v129, 0x3f317217, v142
	v_add_f32_e32 v130, v136, v130
	v_add_f32_e32 v130, v130, v131
	v_mul_f32_e64 v131, |v130|, s31
	v_exp_f32_e32 v131, v131
	v_cmp_lt_f32_e64 s[62:63], |v142|, s20
	v_cndmask_b32_e32 v132, 0, v244, vcc
	v_add_f32_e32 v131, 1.0, v131
	v_cndmask_b32_e64 v129, v142, v129, s[62:63]
	v_cmp_gt_f32_e32 vcc, s34, v131
	v_sub_f32_e32 v129, v129, v132
	v_sub_f32_e32 v127, v127, v129
	v_cndmask_b32_e64 v132, 0, 32, vcc
	v_ldexp_f32 v131, v131, v132
	v_log_f32_e32 v142, v131
	v_min_f32_e32 v129, 0, v130
	ds_read_b128 v[130:133], v88 offset:1792
	ds_read_b128 v[134:137], v88 offset:1808
	v_fmamk_f32 v127, v127, 0x3d800000, v125
	v_mul_f32_e32 v138, 0x3f317217, v142
	v_fma_f32 v143, v142, s35, -v138
	s_waitcnt lgkmcnt(1)
	v_mov_b32_e32 v138, v130
	s_waitcnt lgkmcnt(0)
	v_mov_b32_e32 v139, v134
	v_mov_b32_e32 v134, v131
	v_pk_mul_f32 v[130:131], v[6:7], v[134:135]
	v_mov_b32_e32 v134, v132
	v_pk_fma_f32 v[130:131], v[4:5], v[138:139], v[130:131]
	v_mov_b32_e32 v135, v136
	v_pk_fma_f32 v[134:135], v[2:3], v[134:135], v[130:131]
	v_mov_b32_e32 v136, v133
	ds_read_b128 v[130:133], v88 offset:1824
	ds_read_b128 v[138:141], v88 offset:1840
	v_pk_fma_f32 v[134:135], v[0:1], v[136:137], v[134:135]
	v_fmac_f32_e32 v143, 0x3377d1cf, v142
	v_add_f32_e32 v134, v65, v134
	v_add_f32_e32 v136, v134, v135
	s_waitcnt lgkmcnt(0)
	v_mov_b32_e32 v135, v138
	v_mov_b32_e32 v138, v131
	v_mov_b32_e32 v134, v130
	v_pk_mul_f32 v[130:131], v[78:79], v[138:139]
	v_fmac_f32_e32 v143, 0x3f317217, v142
	v_pk_fma_f32 v[130:131], v[10:11], v[134:135], v[130:131]
	v_mov_b32_e32 v134, v132
	v_mov_b32_e32 v135, v140
	v_pk_fma_f32 v[130:131], v[8:9], v[134:135], v[130:131]
	v_mov_b32_e32 v140, v133
	v_pk_fma_f32 v[130:131], v[80:81], v[140:141], v[130:131]
	v_cmp_lt_f32_e64 s[62:63], |v142|, s20
	v_add_f32_e32 v130, v136, v130
	v_add_f32_e32 v130, v130, v131
	v_mul_f32_e64 v131, |v130|, s31
	v_exp_f32_e32 v131, v131
	v_cndmask_b32_e64 v132, v142, v143, s[62:63]
	v_cndmask_b32_e32 v133, 0, v244, vcc
	v_sub_f32_e32 v132, v132, v133
	v_add_f32_e32 v131, 1.0, v131
	v_cmp_gt_f32_e32 vcc, s34, v131
	v_sub_f32_e32 v129, v129, v132
	v_min_f32_e32 v143, 0, v130
	v_cndmask_b32_e64 v133, 0, 32, vcc
	v_ldexp_f32 v131, v131, v133
	v_log_f32_e32 v142, v131
	ds_read_b128 v[130:133], v88 offset:1856
	ds_read_b128 v[134:137], v88 offset:1872
	v_fmamk_f32 v129, v129, 0x3d800000, v127
	v_mul_f32_e32 v138, 0x3f317217, v142
	v_fma_f32 v144, v142, s35, -v138
	s_waitcnt lgkmcnt(0)
	v_mov_b32_e32 v139, v134
	v_mov_b32_e32 v134, v131
	v_mov_b32_e32 v138, v130
	v_pk_mul_f32 v[130:131], v[6:7], v[134:135]
	v_mov_b32_e32 v134, v132
	v_pk_fma_f32 v[130:131], v[4:5], v[138:139], v[130:131]
	v_mov_b32_e32 v135, v136
	v_pk_fma_f32 v[134:135], v[2:3], v[134:135], v[130:131]
	v_mov_b32_e32 v136, v133
	ds_read_b128 v[130:133], v88 offset:1888
	ds_read_b128 v[138:141], v88 offset:1904
	v_pk_fma_f32 v[134:135], v[0:1], v[136:137], v[134:135]
	v_fmac_f32_e32 v144, 0x3377d1cf, v142
	v_add_f32_e32 v134, v65, v134
	v_add_f32_e32 v136, v134, v135
	s_waitcnt lgkmcnt(0)
; #define LAS __attribute__((address_space(3)))
; __device__ __forceinline__ float log_sigmoid(float x) { return fminf(x, 0.f) - __logf(1.0f + __expf(-fabsf(x))); }
; __device__ __forceinline__ void gla_prep_item(Frame& F, const int jl, const int item) {
;     ...
;     for (int t = 0; t < 32; ++t) { const LAS f32x4* g4 = (const LAS f32x4*)(glr + (half * 32 + t) * 16); float pre = bg;
; #pragma unroll
;         for (int r4 = 0; r4 < 4; ++r4) { const f32x4 g = g4[r4]; pre += g.x * wg[4 * r4] + g.y * wg[4 * r4 + 1] + g.z * wg[4 * r4 + 2] + g.w * wg[4 * r4 + 3]; }
;         run += log_sigmoid(pre) * 0.0625f; cum[t] = run; }
;     tot[half * 256 + d] = run;
;     __syncthreads();
	v_mov_b32_e32 v135, v138
	v_mov_b32_e32 v138, v131
	v_mov_b32_e32 v134, v130
	v_pk_mul_f32 v[130:131], v[78:79], v[138:139]
	v_fmac_f32_e32 v144, 0x3f317217, v142
	v_pk_fma_f32 v[130:131], v[10:11], v[134:135], v[130:131]
	v_mov_b32_e32 v134, v132
	v_mov_b32_e32 v135, v140
	v_pk_fma_f32 v[130:131], v[8:9], v[134:135], v[130:131]
	v_mov_b32_e32 v140, v133
	v_pk_fma_f32 v[130:131], v[80:81], v[140:141], v[130:131]
	v_cmp_lt_f32_e64 s[62:63], |v142|, s20
	v_add_f32_e32 v130, v136, v130
	v_add_f32_e32 v131, v130, v131
	v_mul_f32_e64 v130, |v131|, s31
	v_exp_f32_e32 v130, v130
	v_cndmask_b32_e64 v132, v142, v144, s[62:63]
	v_cndmask_b32_e32 v133, 0, v244, vcc
	v_sub_f32_e32 v132, v132, v133
	v_add_f32_e32 v130, 1.0, v130
	v_cmp_gt_f32_e32 vcc, s34, v130
	v_min_f32_e32 v131, 0, v131
	s_nop 0
	v_cndmask_b32_e64 v133, 0, 32, vcc
	v_ldexp_f32 v130, v130, v133
	v_log_f32_e32 v144, v130
	v_sub_f32_e32 v130, v143, v132
	ds_read_b128 v[132:135], v88 offset:1920
	ds_read_b128 v[136:139], v88 offset:1936
	v_fmamk_f32 v130, v130, 0x3d800000, v129
	v_mul_f32_e32 v140, 0x3f317217, v144
	v_fma_f32 v145, v144, s35, -v140
	s_waitcnt lgkmcnt(1)
	v_mov_b32_e32 v140, v132
	s_waitcnt lgkmcnt(0)
	v_mov_b32_e32 v141, v136
	v_mov_b32_e32 v136, v133
	v_pk_mul_f32 v[132:133], v[6:7], v[136:137]
	v_mov_b32_e32 v136, v134
	v_pk_fma_f32 v[132:133], v[4:5], v[140:141], v[132:133]
	v_mov_b32_e32 v137, v138
	v_pk_fma_f32 v[136:137], v[2:3], v[136:137], v[132:133]
	v_mov_b32_e32 v138, v135
	ds_read_b128 v[132:135], v88 offset:1952
	ds_read_b128 v[140:143], v88 offset:1968
	v_pk_fma_f32 v[136:137], v[0:1], v[138:139], v[136:137]
	v_fmac_f32_e32 v145, 0x3377d1cf, v144
	v_add_f32_e32 v136, v65, v136
	v_add_f32_e32 v138, v136, v137
	s_waitcnt lgkmcnt(0)
	v_mov_b32_e32 v137, v140
	v_mov_b32_e32 v140, v133
	v_mov_b32_e32 v136, v132
	v_pk_mul_f32 v[132:133], v[78:79], v[140:141]
	v_fmac_f32_e32 v145, 0x3f317217, v144
	v_pk_fma_f32 v[132:133], v[10:11], v[136:137], v[132:133]
	v_mov_b32_e32 v136, v134
	v_mov_b32_e32 v137, v142
	v_pk_fma_f32 v[132:133], v[8:9], v[136:137], v[132:133]
	v_mov_b32_e32 v142, v135
	v_pk_fma_f32 v[132:133], v[80:81], v[142:143], v[132:133]
	v_cmp_lt_f32_e64 s[62:63], |v144|, s20
	v_add_f32_e32 v132, v138, v132
	v_add_f32_e32 v132, v132, v133
	v_mul_f32_e64 v133, |v132|, s31
	v_exp_f32_e32 v133, v133
	v_cndmask_b32_e64 v134, v144, v145, s[62:63]
	v_cndmask_b32_e32 v135, 0, v244, vcc
	v_sub_f32_e32 v134, v134, v135
	v_add_f32_e32 v133, 1.0, v133
	v_cmp_gt_f32_e32 vcc, s34, v133
	v_sub_f32_e32 v131, v131, v134
	v_min_f32_e32 v143, 0, v132
	v_cndmask_b32_e64 v135, 0, 32, vcc
	v_ldexp_f32 v133, v133, v135
	v_log_f32_e32 v142, v133
	ds_read_b128 v[132:135], v88 offset:1984
	ds_read_b128 v[136:139], v88 offset:2000
	v_fmamk_f32 v131, v131, 0x3d800000, v130
	v_mul_f32_e32 v140, 0x3f317217, v142
	v_fma_f32 v144, v142, s35, -v140
	s_waitcnt lgkmcnt(0)
	v_mov_b32_e32 v141, v136
	v_mov_b32_e32 v136, v133
	v_mov_b32_e32 v140, v132
	v_pk_mul_f32 v[6:7], v[6:7], v[136:137]
	v_fmac_f32_e32 v144, 0x3377d1cf, v142
	v_pk_fma_f32 v[4:5], v[4:5], v[140:141], v[6:7]
	v_mov_b32_e32 v6, v134
	v_mov_b32_e32 v7, v138
	v_pk_fma_f32 v[6:7], v[2:3], v[6:7], v[4:5]
	v_mov_b32_e32 v138, v135
	ds_read_b128 v[2:5], v88 offset:2016
	ds_read_b128 v[132:135], v88 offset:2032
	v_pk_fma_f32 v[0:1], v[0:1], v[138:139], v[6:7]
	v_fmac_f32_e32 v144, 0x3f317217, v142
	v_add_f32_e32 v0, v65, v0
	v_add_f32_e32 v6, v0, v1
	s_waitcnt lgkmcnt(0)
	v_mov_b32_e32 v1, v132
	v_mov_b32_e32 v132, v3
	v_mov_b32_e32 v0, v2
	v_pk_mul_f32 v[2:3], v[78:79], v[132:133]
	v_cmp_lt_f32_e64 s[62:63], |v142|, s20
	v_pk_fma_f32 v[0:1], v[10:11], v[0:1], v[2:3]
	v_mov_b32_e32 v2, v4
	v_mov_b32_e32 v3, v134
	v_pk_fma_f32 v[0:1], v[8:9], v[2:3], v[0:1]
	v_mov_b32_e32 v134, v5
	v_pk_fma_f32 v[0:1], v[80:81], v[134:135], v[0:1]
	v_cndmask_b32_e64 v2, v142, v144, s[62:63]
	v_add_f32_e32 v0, v6, v0
	v_add_f32_e32 v0, v0, v1
	v_mul_f32_e64 v1, |v0|, s31
	v_exp_f32_e32 v1, v1
	v_cndmask_b32_e32 v3, 0, v244, vcc
	v_sub_f32_e32 v2, v2, v3
	v_sub_f32_e32 v2, v143, v2
	v_add_f32_e32 v1, 1.0, v1
	v_cmp_gt_f32_e32 vcc, s34, v1
	v_fmamk_f32 v79, v2, 0x3d800000, v131
	v_min_f32_e32 v0, 0, v0
	v_cndmask_b32_e64 v3, 0, 32, vcc
	v_ldexp_f32 v1, v1, v3
	v_log_f32_e32 v1, v1
	s_nop 0
	v_mul_f32_e32 v2, 0x3f317217, v1
	v_fma_f32 v2, v1, s35, -v2
	v_fmac_f32_e32 v2, 0x3377d1cf, v1
	v_fmac_f32_e32 v2, 0x3f317217, v1
	v_cmp_lt_f32_e64 s[62:63], |v1|, s20
	s_nop 1
	v_cndmask_b32_e64 v1, v1, v2, s[62:63]
	v_cndmask_b32_e32 v2, 0, v244, vcc
	v_sub_f32_e32 v1, v1, v2
	v_sub_f32_e32 v0, v0, v1
	v_fmamk_f32 v78, v0, 0x3d800000, v79
	ds_write_b32 v89, v78 offset:4096
	s_waitcnt lgkmcnt(0)
	s_barrier
; #define LAS __attribute__((address_space(3)))
; __device__ __forceinline__ float bf2f(unsigned short v) { return __uint_as_float((unsigned)v << 16); }
; __device__ __forceinline__ void gla_prep_item(Frame& F, const int jl, const int item) {
;     ...
;     const float off = half ? tot[d] : 0.f, blast = tot[d] + tot[256 + d];
;     const float elast = __expf(blast);
;     unsigned kow[16];
; #pragma unroll
;     for (int t = 0; t < 32; ++t) { const float bb = cum[t] + off; const int tok = half * 32 + t;
;         const float qv = bf2f(*(const LAS bf16*)(qs + tok * QP + d * 2)), kvv = bf2f(*(const LAS bf16*)(ks + tok * QP + d * 2));
;         const float eb = __expf(bb), ki = kvv * __builtin_amdgcn_rcpf(eb);
;         const unsigned qk = pk2(qv * 0.0625f * eb, ki);
;         *(LAS bf16*)(qs + tok * QP + d * 2) = (bf16)(qk & 0xffff); *(LAS bf16*)(ks + tok * QP + d * 2) = (bf16)(qk >> 16);
;         const unsigned kob = pk2(ki * elast, 0.f) & 0xffff;
;         if (t & 1) kow[t >> 1] |= kob << 16; else kow[t >> 1] = kob; }
	ds_read2st64_b32 v[0:1], v90 offset0:16 offset1:20
	s_waitcnt lgkmcnt(0)
	v_cndmask_b32_e64 v80, v0, 0, s[42:43]
	v_add_f32_e32 v0, v0, v1
	v_mul_f32_e32 v0, 0x3fb8aa3b, v0
	v_exp_f32_e32 v65, v0
	v_add_f32_e32 v0, v104, v80
	v_mul_f32_e32 v0, 0x3fb8aa3b, v0
	v_exp_f32_e32 v0, v0
	ds_read_u16 v1, v91 offset:8192
	ds_read_u16 v4, v91 offset:8720
	ds_read_u16 v5, v91 offset:9248
	ds_read_u16 v6, v91 offset:9776
	ds_read_u16 v7, v91 offset:10304
	ds_read_u16 v8, v91 offset:10832
	ds_read_u16 v9, v91 offset:11360
	ds_read_u16 v10, v91 offset:11888
	s_waitcnt lgkmcnt(7)
	v_lshlrev_b32_e32 v2, 16, v1
	ds_read_u16 v3, v91 offset:41984
	ds_read_u16 v11, v91 offset:42512
	ds_read_u16 v81, v91 offset:43040
	ds_read_u16 v104, v91 offset:43568
	ds_read_u16 v132, v91 offset:44096
	ds_read_u16 v133, v91 offset:44624
	ds_read_u16 v134, v91 offset:45152
	ds_read_u16 v135, v91 offset:45680
	v_rcp_f32_e32 v1, v0
	s_waitcnt lgkmcnt(7)
	v_lshlrev_b32_e32 v3, 16, v3
	v_mul_f32_e32 v2, 0x3d800000, v2
	v_pk_mul_f32 v[0:1], v[0:1], v[2:3]
	s_nop 0
	v_cvt_pk_bf16_f32 v0, v0, v1
	ds_write_b16 v91, v0 offset:8192
	ds_write_b16_d16_hi v91, v0 offset:41984
	v_add_f32_e32 v0, v67, v80
	v_mul_f32_e32 v0, 0x3fb8aa3b, v0
	v_exp_f32_e32 v0, v0
	v_mul_f32_e32 v1, v65, v1
	v_cvt_pk_bf16_f32 v1, v1, 0
	v_and_b32_e32 v67, 0xffff, v1
	v_rcp_f32_e32 v1, v0
	v_lshlrev_b32_e32 v2, 16, v4
	s_waitcnt lgkmcnt(8)
	v_lshlrev_b32_e32 v3, 16, v11
	v_mul_f32_e32 v2, 0x3d800000, v2
	v_pk_mul_f32 v[0:1], v[0:1], v[2:3]
	s_nop 0
	v_cvt_pk_bf16_f32 v0, v0, v1
	ds_write_b16 v91, v0 offset:8720
	ds_write_b16_d16_hi v91, v0 offset:42512
	v_add_f32_e32 v0, v69, v80
	v_mul_f32_e32 v0, 0x3fb8aa3b, v0
	v_exp_f32_e32 v2, v0
	v_mul_f32_e32 v0, v65, v1
	v_lshlrev_b32_e32 v1, 16, v5
	s_waitcnt lgkmcnt(9)
	v_lshlrev_b32_e32 v5, 16, v81
	v_rcp_f32_e32 v3, v2
	v_mul_f32_e32 v4, 0x3d800000, v1
	v_cvt_pk_bf16_f32 v0, v0, 0
	v_lshl_or_b32 v0, v0, 16, v67
	v_pk_mul_f32 v[2:3], v[2:3], v[4:5]
	v_lshlrev_b32_e32 v4, 16, v6
	v_cvt_pk_bf16_f32 v1, v2, v3
	ds_write_b16 v91, v1 offset:9248
	ds_write_b16_d16_hi v91, v1 offset:43040
	v_add_f32_e32 v1, v105, v80
	v_mul_f32_e32 v1, 0x3fb8aa3b, v1
	v_exp_f32_e32 v2, v1
	v_mul_f32_e32 v1, v65, v3
	s_waitcnt lgkmcnt(10)
	v_lshlrev_b32_e32 v5, 16, v104
	v_mul_f32_e32 v4, 0x3d800000, v4
	v_rcp_f32_e32 v3, v2
	v_cvt_pk_bf16_f32 v1, v1, 0
	v_and_b32_e32 v1, 0xffff, v1
	v_pk_mul_f32 v[2:3], v[2:3], v[4:5]
	s_nop 0
	v_cvt_pk_bf16_f32 v2, v2, v3
	ds_write_b16 v91, v2 offset:9776
	ds_write_b16_d16_hi v91, v2 offset:43568
	v_add_f32_e32 v2, v106, v80
	v_mul_f32_e32 v2, 0x3fb8aa3b, v2
	v_exp_f32_e32 v2, v2
	v_mul_f32_e32 v3, v65, v3
	v_cvt_pk_bf16_f32 v3, v3, 0
	v_lshl_or_b32 v1, v3, 16, v1
	v_rcp_f32_e32 v3, v2
	v_lshlrev_b32_e32 v4, 16, v7
	s_waitcnt lgkmcnt(11)
	v_lshlrev_b32_e32 v5, 16, v132
	v_mul_f32_e32 v4, 0x3d800000, v4
	v_pk_mul_f32 v[2:3], v[2:3], v[4:5]
	v_lshlrev_b32_e32 v4, 16, v8
	v_cvt_pk_bf16_f32 v2, v2, v3
	ds_write_b16 v91, v2 offset:10304
	ds_write_b16_d16_hi v91, v2 offset:44096
	v_add_f32_e32 v2, v107, v80
	v_mul_f32_e32 v2, 0x3fb8aa3b, v2
	v_exp_f32_e32 v2, v2
	v_mul_f32_e32 v3, v65, v3
	v_cvt_pk_bf16_f32 v3, v3, 0
	v_and_b32_e32 v6, 0xffff, v3
	v_rcp_f32_e32 v3, v2
	s_waitcnt lgkmcnt(12)
	v_lshlrev_b32_e32 v5, 16, v133
	v_mul_f32_e32 v4, 0x3d800000, v4
	s_waitcnt lgkmcnt(11)
	v_lshlrev_b32_e32 v7, 16, v134
	v_pk_mul_f32 v[2:3], v[2:3], v[4:5]
	s_nop 0
	v_cvt_pk_bf16_f32 v2, v2, v3
	ds_write_b16 v91, v2 offset:10832
	ds_write_b16_d16_hi v91, v2 offset:44624
	v_add_f32_e32 v2, v108, v80
	v_mul_f32_e32 v2, 0x3fb8aa3b, v2
	v_exp_f32_e32 v4, v2
	v_mul_f32_e32 v2, v65, v3
	v_cvt_pk_bf16_f32 v2, v2, 0
	v_lshlrev_b32_e32 v3, 16, v9
	v_rcp_f32_e32 v5, v4
	v_lshl_or_b32 v2, v2, 16, v6
	v_mul_f32_e32 v6, 0x3d800000, v3
	v_pk_mul_f32 v[4:5], v[4:5], v[6:7]
	s_nop 0
	v_cvt_pk_bf16_f32 v3, v4, v5
	ds_write_b16 v91, v3 offset:11360
	ds_write_b16_d16_hi v91, v3 offset:45152
	v_add_f32_e32 v3, v110, v80
	v_mul_f32_e32 v3, 0x3fb8aa3b, v3
	v_exp_f32_e32 v4, v3
	v_mul_f32_e32 v3, v65, v5
	v_lshlrev_b32_e32 v6, 16, v10
	s_waitcnt lgkmcnt(14)
	v_lshlrev_b32_e32 v7, 16, v135
	v_rcp_f32_e32 v5, v4
	v_mul_f32_e32 v6, 0x3d800000, v6
	v_cvt_pk_bf16_f32 v3, v3, 0
	v_and_b32_e32 v3, 0xffff, v3
	v_pk_mul_f32 v[4:5], v[4:5], v[6:7]
	s_nop 0
	v_cvt_pk_bf16_f32 v4, v4, v5
	ds_write_b16 v91, v4 offset:11888
	ds_write_b16_d16_hi v91, v4 offset:45680
	v_mul_f32_e32 v4, v65, v5
	v_cvt_pk_bf16_f32 v4, v4, 0
	v_lshl_or_b32 v3, v4, 16, v3
	v_add_f32_e32 v4, v112, v80
	v_mul_f32_e32 v4, 0x3fb8aa3b, v4
	v_exp_f32_e32 v4, v4
	ds_read_u16 v5, v91 offset:12416
	ds_read_u16 v8, v91 offset:12944
	ds_read_u16 v9, v91 offset:13472
	ds_read_u16 v10, v91 offset:14000
	ds_read_u16 v11, v91 offset:14528
	ds_read_u16 v67, v91 offset:15056
	ds_read_u16 v69, v91 offset:15584
	ds_read_u16 v81, v91 offset:16112
	s_waitcnt lgkmcnt(7)
	v_lshlrev_b32_e32 v6, 16, v5
	ds_read_u16 v7, v91 offset:46208
	ds_read_u16 v104, v91 offset:46736
	ds_read_u16 v105, v91 offset:47264
	ds_read_u16 v106, v91 offset:47792
	ds_read_u16 v107, v91 offset:48320
	ds_read_u16 v108, v91 offset:48848
	ds_read_u16 v110, v91 offset:49376
	ds_read_u16 v112, v91 offset:49904
	v_rcp_f32_e32 v5, v4
	s_waitcnt lgkmcnt(7)
	v_lshlrev_b32_e32 v7, 16, v7
	v_mul_f32_e32 v6, 0x3d800000, v6
	v_pk_mul_f32 v[4:5], v[4:5], v[6:7]
	s_nop 0
	v_cvt_pk_bf16_f32 v4, v4, v5
	ds_write_b16 v91, v4 offset:12416
	ds_write_b16_d16_hi v91, v4 offset:46208
	v_add_f32_e32 v4, v109, v80
	v_mul_f32_e32 v4, 0x3fb8aa3b, v4
	v_exp_f32_e32 v4, v4
	v_mul_f32_e32 v5, v65, v5
	v_cvt_pk_bf16_f32 v5, v5, 0
	v_and_b32_e32 v109, 0xffff, v5
	v_rcp_f32_e32 v5, v4
	v_lshlrev_b32_e32 v6, 16, v8
	s_waitcnt lgkmcnt(8)
; #define LAS __attribute__((address_space(3)))
; __device__ __forceinline__ float bf2f(unsigned short v) { return __uint_as_float((unsigned)v << 16); }
; __device__ __forceinline__ void gla_prep_item(Frame& F, const int jl, const int item) {
;     ...
;     for (int t = 0; t < 32; ++t) { const float bb = cum[t] + off; const int tok = half * 32 + t;
;         const float qv = bf2f(*(const LAS bf16*)(qs + tok * QP + d * 2)), kvv = bf2f(*(const LAS bf16*)(ks + tok * QP + d * 2));
;         const float eb = __expf(bb), ki = kvv * __builtin_amdgcn_rcpf(eb);
;         const unsigned qk = pk2(qv * 0.0625f * eb, ki);
;         *(LAS bf16*)(qs + tok * QP + d * 2) = (bf16)(qk & 0xffff); *(LAS bf16*)(ks + tok * QP + d * 2) = (bf16)(qk >> 16);
;         const unsigned kob = pk2(ki * elast, 0.f) & 0xffff;
;         if (t & 1) kow[t >> 1] |= kob << 16; else kow[t >> 1] = kob; }
	v_lshlrev_b32_e32 v7, 16, v104
	v_mul_f32_e32 v6, 0x3d800000, v6
	v_pk_mul_f32 v[4:5], v[4:5], v[6:7]
	s_nop 0
	v_cvt_pk_bf16_f32 v4, v4, v5
	ds_write_b16 v91, v4 offset:12944
	ds_write_b16_d16_hi v91, v4 offset:46736
	v_add_f32_e32 v4, v111, v80
	v_mul_f32_e32 v4, 0x3fb8aa3b, v4
	v_exp_f32_e32 v6, v4
	v_mul_f32_e32 v4, v65, v5
	v_lshlrev_b32_e32 v5, 16, v9
	s_waitcnt lgkmcnt(9)
	v_lshlrev_b32_e32 v9, 16, v105
	v_rcp_f32_e32 v7, v6
	v_mul_f32_e32 v8, 0x3d800000, v5
	v_cvt_pk_bf16_f32 v4, v4, 0
	v_lshl_or_b32 v4, v4, 16, v109
	v_pk_mul_f32 v[6:7], v[6:7], v[8:9]
	v_lshlrev_b32_e32 v8, 16, v10
	v_cvt_pk_bf16_f32 v5, v6, v7
	ds_write_b16 v91, v5 offset:13472
	ds_write_b16_d16_hi v91, v5 offset:47264
	v_add_f32_e32 v5, v113, v80
	v_mul_f32_e32 v5, 0x3fb8aa3b, v5
	v_exp_f32_e32 v6, v5
	v_mul_f32_e32 v5, v65, v7
	s_waitcnt lgkmcnt(10)
	v_lshlrev_b32_e32 v9, 16, v106
	v_mul_f32_e32 v8, 0x3d800000, v8
	v_rcp_f32_e32 v7, v6
	v_cvt_pk_bf16_f32 v5, v5, 0
	v_and_b32_e32 v5, 0xffff, v5
	v_pk_mul_f32 v[6:7], v[6:7], v[8:9]
	s_nop 0
	v_cvt_pk_bf16_f32 v6, v6, v7
	ds_write_b16 v91, v6 offset:14000
	ds_write_b16_d16_hi v91, v6 offset:47792
	v_add_f32_e32 v6, v114, v80
	v_mul_f32_e32 v6, 0x3fb8aa3b, v6
	v_exp_f32_e32 v6, v6
	v_mul_f32_e32 v7, v65, v7
	v_cvt_pk_bf16_f32 v7, v7, 0
	v_lshl_or_b32 v5, v7, 16, v5
	v_rcp_f32_e32 v7, v6
	v_lshlrev_b32_e32 v8, 16, v11
	s_waitcnt lgkmcnt(11)
	v_lshlrev_b32_e32 v9, 16, v107
	v_mul_f32_e32 v8, 0x3d800000, v8
	v_pk_mul_f32 v[6:7], v[6:7], v[8:9]
	v_lshlrev_b32_e32 v8, 16, v67
	v_cvt_pk_bf16_f32 v6, v6, v7
	ds_write_b16 v91, v6 offset:14528
	ds_write_b16_d16_hi v91, v6 offset:48320
	v_add_f32_e32 v6, v115, v80
	v_mul_f32_e32 v6, 0x3fb8aa3b, v6
	v_exp_f32_e32 v6, v6
	v_mul_f32_e32 v7, v65, v7
	v_cvt_pk_bf16_f32 v7, v7, 0
	v_and_b32_e32 v10, 0xffff, v7
	v_rcp_f32_e32 v7, v6
	s_waitcnt lgkmcnt(12)
	v_lshlrev_b32_e32 v9, 16, v108
	v_mul_f32_e32 v8, 0x3d800000, v8
	s_waitcnt lgkmcnt(11)
	v_lshlrev_b32_e32 v11, 16, v110
	v_pk_mul_f32 v[6:7], v[6:7], v[8:9]
	s_nop 0
	v_cvt_pk_bf16_f32 v6, v6, v7
	ds_write_b16 v91, v6 offset:15056
	ds_write_b16_d16_hi v91, v6 offset:48848
	v_add_f32_e32 v6, v116, v80
	v_mul_f32_e32 v6, 0x3fb8aa3b, v6
	v_exp_f32_e32 v8, v6
	v_mul_f32_e32 v6, v65, v7
	v_cvt_pk_bf16_f32 v6, v6, 0
	v_lshlrev_b32_e32 v7, 16, v69
	v_rcp_f32_e32 v9, v8
	v_lshl_or_b32 v6, v6, 16, v10
	v_mul_f32_e32 v10, 0x3d800000, v7
	v_pk_mul_f32 v[8:9], v[8:9], v[10:11]
	s_nop 0
	v_cvt_pk_bf16_f32 v7, v8, v9
	ds_write_b16 v91, v7 offset:15584
	ds_write_b16_d16_hi v91, v7 offset:49376
	v_add_f32_e32 v7, v118, v80
	v_mul_f32_e32 v7, 0x3fb8aa3b, v7
	v_exp_f32_e32 v8, v7
	v_mul_f32_e32 v7, v65, v9
	v_lshlrev_b32_e32 v10, 16, v81
	s_waitcnt lgkmcnt(14)
	v_lshlrev_b32_e32 v11, 16, v112
	v_rcp_f32_e32 v9, v8
	v_mul_f32_e32 v10, 0x3d800000, v10
	v_cvt_pk_bf16_f32 v7, v7, 0
	v_and_b32_e32 v7, 0xffff, v7
	v_pk_mul_f32 v[8:9], v[8:9], v[10:11]
	s_nop 0
	v_cvt_pk_bf16_f32 v8, v8, v9
	ds_write_b16 v91, v8 offset:16112
	ds_write_b16_d16_hi v91, v8 offset:49904
	v_mul_f32_e32 v8, v65, v9
	v_cvt_pk_bf16_f32 v8, v8, 0
	v_lshl_or_b32 v7, v8, 16, v7
	v_add_f32_e32 v8, v120, v80
	v_mul_f32_e32 v8, 0x3fb8aa3b, v8
	v_exp_f32_e32 v8, v8
	ds_read_u16 v9, v91 offset:16640
	ds_read_u16 v67, v91 offset:17168
	ds_read_u16 v69, v91 offset:17696
	ds_read_u16 v81, v91 offset:18224
	ds_read_u16 v106, v91 offset:18752
	ds_read_u16 v107, v91 offset:19280
	ds_read_u16 v108, v91 offset:19808
	ds_read_u16 v109, v91 offset:20336
	s_waitcnt lgkmcnt(7)
	v_lshlrev_b32_e32 v10, 16, v9
	ds_read_u16 v11, v91 offset:50432
	ds_read_u16 v104, v91 offset:50960
	ds_read_u16 v105, v91 offset:51488
	ds_read_u16 v110, v91 offset:52016
	ds_read_u16 v111, v91 offset:52544
	ds_read_u16 v112, v91 offset:53072
	ds_read_u16 v113, v91 offset:53600
	ds_read_u16 v114, v91 offset:54128
	v_rcp_f32_e32 v9, v8
	s_waitcnt lgkmcnt(7)
	v_lshlrev_b32_e32 v11, 16, v11
	v_mul_f32_e32 v10, 0x3d800000, v10
	s_waitcnt lgkmcnt(5)
	v_lshlrev_b32_e32 v105, 16, v105
	v_pk_mul_f32 v[8:9], v[8:9], v[10:11]
	v_lshlrev_b32_e32 v10, 16, v67
	v_cvt_pk_bf16_f32 v8, v8, v9
	ds_write_b16 v91, v8 offset:16640
	ds_write_b16_d16_hi v91, v8 offset:50432
	v_add_f32_e32 v8, v117, v80
	v_mul_f32_e32 v8, 0x3fb8aa3b, v8
	v_exp_f32_e32 v8, v8
	v_mul_f32_e32 v9, v65, v9
	v_cvt_pk_bf16_f32 v9, v9, 0
	v_and_b32_e32 v115, 0xffff, v9
	v_rcp_f32_e32 v9, v8
	v_lshlrev_b32_e32 v11, 16, v104
	v_mul_f32_e32 v10, 0x3d800000, v10
	v_lshlrev_b32_e32 v67, 16, v81
	v_pk_mul_f32 v[8:9], v[8:9], v[10:11]
	s_nop 0
	v_cvt_pk_bf16_f32 v8, v8, v9
	ds_write_b16 v91, v8 offset:17168
	ds_write_b16_d16_hi v91, v8 offset:50960
	v_add_f32_e32 v8, v119, v80
	v_mul_f32_e32 v8, 0x3fb8aa3b, v8
	v_exp_f32_e32 v10, v8
	v_mul_f32_e32 v8, v65, v9
	v_lshlrev_b32_e32 v9, 16, v69
	v_mul_f32_e32 v104, 0x3d800000, v9
	v_rcp_f32_e32 v11, v10
	v_lshlrev_b32_e32 v69, 16, v107
	s_waitcnt lgkmcnt(5)
; #define LAS __attribute__((address_space(3)))
; __device__ __forceinline__ float bf2f(unsigned short v) { return __uint_as_float((unsigned)v << 16); }
; __device__ __forceinline__ void gla_prep_item(Frame& F, const int jl, const int item) {
;     ...
;     for (int t = 0; t < 32; ++t) { const float bb = cum[t] + off; const int tok = half * 32 + t;
;         const float qv = bf2f(*(const LAS bf16*)(qs + tok * QP + d * 2)), kvv = bf2f(*(const LAS bf16*)(ks + tok * QP + d * 2));
;         const float eb = __expf(bb), ki = kvv * __builtin_amdgcn_rcpf(eb);
;         const unsigned qk = pk2(qv * 0.0625f * eb, ki);
;         *(LAS bf16*)(qs + tok * QP + d * 2) = (bf16)(qk & 0xffff); *(LAS bf16*)(ks + tok * QP + d * 2) = (bf16)(qk >> 16);
;         const unsigned kob = pk2(ki * elast, 0.f) & 0xffff;
;         if (t & 1) kow[t >> 1] |= kob << 16; else kow[t >> 1] = kob; }
	v_lshlrev_b32_e32 v107, 16, v113
	v_cvt_pk_bf16_f32 v8, v8, 0
	v_pk_mul_f32 v[10:11], v[10:11], v[104:105]
	v_lshlrev_b32_e32 v105, 16, v110
	v_cvt_pk_bf16_f32 v9, v10, v11
	ds_write_b16 v91, v9 offset:17696
	ds_write_b16_d16_hi v91, v9 offset:51488
	v_add_f32_e32 v9, v121, v80
	v_mul_f32_e32 v9, 0x3fb8aa3b, v9
	v_exp_f32_e32 v10, v9
	v_mul_f32_e32 v9, v65, v11
	v_mul_f32_e32 v104, 0x3d800000, v67
	v_cvt_pk_bf16_f32 v9, v9, 0
	v_rcp_f32_e32 v11, v10
	v_and_b32_e32 v9, 0xffff, v9
	v_lshlrev_b32_e32 v67, 16, v106
	v_lshl_or_b32 v8, v8, 16, v115
	v_pk_mul_f32 v[10:11], v[10:11], v[104:105]
	v_lshlrev_b32_e32 v105, 16, v111
	v_cvt_pk_bf16_f32 v10, v10, v11
	ds_write_b16 v91, v10 offset:18224
	ds_write_b16_d16_hi v91, v10 offset:52016
	v_add_f32_e32 v10, v122, v80
	v_mul_f32_e32 v10, 0x3fb8aa3b, v10
	v_exp_f32_e32 v10, v10
	v_mul_f32_e32 v11, v65, v11
	v_cvt_pk_bf16_f32 v11, v11, 0
	v_lshl_or_b32 v9, v11, 16, v9
	v_rcp_f32_e32 v11, v10
	v_mul_f32_e32 v104, 0x3d800000, v67
	v_pk_mul_f32 v[10:11], v[10:11], v[104:105]
	s_nop 0
	v_cvt_pk_bf16_f32 v10, v10, v11
	ds_write_b16 v91, v10 offset:18752
	ds_write_b16_d16_hi v91, v10 offset:52544
	v_add_f32_e32 v10, v123, v80
	v_mul_f32_e32 v10, 0x3fb8aa3b, v10
	v_exp_f32_e32 v10, v10
	v_mul_f32_e32 v11, v65, v11
	v_cvt_pk_bf16_f32 v11, v11, 0
	v_and_b32_e32 v67, 0xffff, v11
	v_rcp_f32_e32 v11, v10
	v_lshlrev_b32_e32 v105, 16, v112
	v_mul_f32_e32 v104, 0x3d800000, v69
	v_pk_mul_f32 v[10:11], v[10:11], v[104:105]
	s_nop 0
	v_cvt_pk_bf16_f32 v10, v10, v11
	ds_write_b16 v91, v10 offset:19280
	ds_write_b16_d16_hi v91, v10 offset:53072
	v_add_f32_e32 v10, v124, v80
	v_mul_f32_e32 v10, 0x3fb8aa3b, v10
	v_exp_f32_e32 v104, v10
	v_mul_f32_e32 v10, v65, v11
	v_lshlrev_b32_e32 v11, 16, v108
	v_mul_f32_e32 v106, 0x3d800000, v11
	v_rcp_f32_e32 v105, v104
	v_cvt_pk_bf16_f32 v10, v10, 0
	v_lshl_or_b32 v10, v10, 16, v67
	v_lshlrev_b32_e32 v67, 16, v109
	v_pk_mul_f32 v[104:105], v[104:105], v[106:107]
	s_waitcnt lgkmcnt(12)
	v_lshlrev_b32_e32 v107, 16, v114
	v_cvt_pk_bf16_f32 v11, v104, v105
	ds_write_b16 v91, v11 offset:19808
	ds_write_b16_d16_hi v91, v11 offset:53600
	v_add_f32_e32 v11, v126, v80
	v_mul_f32_e32 v11, 0x3fb8aa3b, v11
	v_exp_f32_e32 v104, v11
	v_mul_f32_e32 v11, v65, v105
	v_mul_f32_e32 v106, 0x3d800000, v67
	v_cvt_pk_bf16_f32 v11, v11, 0
	v_rcp_f32_e32 v105, v104
	v_and_b32_e32 v11, 0xffff, v11
	v_pk_mul_f32 v[104:105], v[104:105], v[106:107]
	s_nop 0
	v_cvt_pk_bf16_f32 v67, v104, v105
	ds_write_b16 v91, v67 offset:20336
	ds_write_b16_d16_hi v91, v67 offset:54128
	v_mul_f32_e32 v67, v65, v105
	v_cvt_pk_bf16_f32 v67, v67, 0
	v_lshl_or_b32 v11, v67, 16, v11
	v_add_f32_e32 v67, v128, v80
	v_mul_f32_e32 v67, 0x3fb8aa3b, v67
	v_exp_f32_e32 v104, v67
	ds_read_u16 v67, v91 offset:20864
	ds_read_u16 v69, v91 offset:21392
	ds_read_u16 v81, v91 offset:21920
	ds_read_u16 v110, v91 offset:22448
	ds_read_u16 v111, v91 offset:22976
	ds_read_u16 v112, v91 offset:23504
	ds_read_u16 v113, v91 offset:24032
	ds_read_u16 v114, v91 offset:24560
	s_waitcnt lgkmcnt(7)
	v_lshlrev_b32_e32 v67, 16, v67
	ds_read_u16 v106, v91 offset:54656
	ds_read_u16 v108, v91 offset:55184
	ds_read_u16 v109, v91 offset:55712
	ds_read_u16 v115, v91 offset:56240
	ds_read_u16 v116, v91 offset:56768
	ds_read_u16 v117, v91 offset:57296
	ds_read_u16 v118, v91 offset:57824
	ds_read_u16 v119, v91 offset:58352
	v_rcp_f32_e32 v105, v104
	s_waitcnt lgkmcnt(7)
	v_lshlrev_b32_e32 v107, 16, v106
	v_mul_f32_e32 v106, 0x3d800000, v67
	v_lshlrev_b32_e32 v69, 16, v69
	v_pk_mul_f32 v[104:105], v[104:105], v[106:107]
	s_waitcnt lgkmcnt(6)
	v_lshlrev_b32_e32 v107, 16, v108
	v_cvt_pk_bf16_f32 v67, v104, v105
	ds_write_b16 v91, v67 offset:20864
	ds_write_b16_d16_hi v91, v67 offset:54656
	v_add_f32_e32 v67, v125, v80
	v_mul_f32_e32 v67, 0x3fb8aa3b, v67
	v_exp_f32_e32 v104, v67
	v_mul_f32_e32 v67, v65, v105
	v_mul_f32_e32 v106, 0x3d800000, v69
	v_cvt_pk_bf16_f32 v67, v67, 0
	v_rcp_f32_e32 v105, v104
	v_and_b32_e32 v67, 0xffff, v67
	s_waitcnt lgkmcnt(7)
; #define LAS __attribute__((address_space(3)))
; __device__ __forceinline__ float bf2f(unsigned short v) { return __uint_as_float((unsigned)v << 16); }
; __device__ __forceinline__ void gla_prep_item(Frame& F, const int jl, const int item) {
;     ...
;     for (int t = 0; t < 32; ++t) { const float bb = cum[t] + off; const int tok = half * 32 + t;
;         const float qv = bf2f(*(const LAS bf16*)(qs + tok * QP + d * 2)), kvv = bf2f(*(const LAS bf16*)(ks + tok * QP + d * 2));
;         const float eb = __expf(bb), ki = kvv * __builtin_amdgcn_rcpf(eb);
;         const unsigned qk = pk2(qv * 0.0625f * eb, ki);
;         *(LAS bf16*)(qs + tok * QP + d * 2) = (bf16)(qk & 0xffff); *(LAS bf16*)(ks + tok * QP + d * 2) = (bf16)(qk >> 16);
;         const unsigned kob = pk2(ki * elast, 0.f) & 0xffff;
;         if (t & 1) kow[t >> 1] |= kob << 16; else kow[t >> 1] = kob; }
;     { v4u* dst = (v4u*)(KOT + ((size_t)item * 256 + d) * 64 + half * 32);
; #pragma unroll
;       for (int q = 0; q < 4; ++q) dst[q] = (v4u){kow[4 * q], kow[4 * q + 1], kow[4 * q + 2], kow[4 * q + 3]}; }
;     if (half == 0) DEC[(size_t)item * 256 + d] = elast;
	v_lshlrev_b32_e32 v109, 16, v109
	v_pk_mul_f32 v[104:105], v[104:105], v[106:107]
	s_nop 0
	v_cvt_pk_bf16_f32 v69, v104, v105
	ds_write_b16 v91, v69 offset:21392
	ds_write_b16_d16_hi v91, v69 offset:55184
	v_add_f32_e32 v69, v127, v80
	v_mul_f32_e32 v69, 0x3fb8aa3b, v69
	v_exp_f32_e32 v106, v69
	v_mul_f32_e32 v69, v65, v105
	v_cvt_pk_bf16_f32 v69, v69, 0
	v_lshl_or_b32 v104, v69, 16, v67
	v_rcp_f32_e32 v107, v106
	v_lshlrev_b32_e32 v67, 16, v81
	v_mul_f32_e32 v108, 0x3d800000, v67
	v_lshlrev_b32_e32 v69, 16, v110
	v_pk_mul_f32 v[106:107], v[106:107], v[108:109]
	s_waitcnt lgkmcnt(8)
	v_lshlrev_b32_e32 v109, 16, v115
	v_cvt_pk_bf16_f32 v67, v106, v107
	ds_write_b16 v91, v67 offset:21920
	ds_write_b16_d16_hi v91, v67 offset:55712
	v_add_f32_e32 v67, v129, v80
	v_mul_f32_e32 v67, 0x3fb8aa3b, v67
	v_exp_f32_e32 v106, v67
	v_mul_f32_e32 v67, v65, v107
	v_mul_f32_e32 v108, 0x3d800000, v69
	v_cvt_pk_bf16_f32 v67, v67, 0
	v_rcp_f32_e32 v107, v106
	v_and_b32_e32 v67, 0xffff, v67
	s_waitcnt lgkmcnt(6)
	v_lshlrev_b32_e32 v81, 16, v119
	v_pk_mul_f32 v[106:107], v[106:107], v[108:109]
	s_nop 0
	v_cvt_pk_bf16_f32 v69, v106, v107
	ds_write_b16 v91, v69 offset:22448
	ds_write_b16_d16_hi v91, v69 offset:56240
	v_add_f32_e32 v69, v130, v80
	v_mul_f32_e32 v69, 0x3fb8aa3b, v69
	v_exp_f32_e32 v106, v69
	v_mul_f32_e32 v69, v65, v107
	v_cvt_pk_bf16_f32 v69, v69, 0
	v_lshl_or_b32 v105, v69, 16, v67
	v_rcp_f32_e32 v107, v106
	v_lshlrev_b32_e32 v67, 16, v111
	v_lshlrev_b32_e32 v109, 16, v116
	v_mul_f32_e32 v108, 0x3d800000, v67
	v_pk_mul_f32 v[106:107], v[106:107], v[108:109]
	v_lshlrev_b32_e32 v69, 16, v112
	v_cvt_pk_bf16_f32 v67, v106, v107
	ds_write_b16 v91, v67 offset:22976
	ds_write_b16_d16_hi v91, v67 offset:56768
	v_add_f32_e32 v67, v80, v131
	v_mul_f32_e32 v67, 0x3fb8aa3b, v67
	v_exp_f32_e32 v106, v67
	v_mul_f32_e32 v67, v65, v107
	v_lshlrev_b32_e32 v109, 16, v117
	v_mul_f32_e32 v108, 0x3d800000, v69
	v_rcp_f32_e32 v107, v106
	v_cvt_pk_bf16_f32 v67, v67, 0
	v_and_b32_e32 v67, 0xffff, v67
	v_lshlrev_b32_e32 v111, 16, v118
	v_pk_mul_f32 v[106:107], v[106:107], v[108:109]
	s_nop 0
	v_cvt_pk_bf16_f32 v69, v106, v107
	ds_write_b16 v91, v69 offset:23504
	ds_write_b16_d16_hi v91, v69 offset:57296
	v_add_f32_e32 v69, v80, v79
	v_mul_f32_e32 v69, 0x3fb8aa3b, v69
	v_exp_f32_e32 v108, v69
	v_mul_f32_e32 v69, v65, v107
	v_cvt_pk_bf16_f32 v69, v69, 0
	v_lshl_or_b32 v106, v69, 16, v67
	v_rcp_f32_e32 v109, v108
	v_lshlrev_b32_e32 v67, 16, v113
	v_mul_f32_e32 v110, 0x3d800000, v67
	v_lshlrev_b32_e32 v69, 16, v114
	v_pk_mul_f32 v[108:109], v[108:109], v[110:111]
	s_nop 0
	v_cvt_pk_bf16_f32 v67, v108, v109
	ds_write_b16 v91, v67 offset:24032
	ds_write_b16_d16_hi v91, v67 offset:57824
	v_add_f32_e32 v67, v80, v78
	v_mul_f32_e32 v67, 0x3fb8aa3b, v67
	v_exp_f32_e32 v78, v67
	v_mul_f32_e32 v80, 0x3d800000, v69
	v_mul_f32_e32 v67, v65, v109
	v_cvt_pk_bf16_f32 v67, v67, 0
	v_rcp_f32_e32 v79, v78
	v_and_b32_e32 v67, 0xffff, v67
	v_pk_mul_f32 v[78:79], v[78:79], v[80:81]
	s_nop 0
	v_cvt_pk_bf16_f32 v69, v78, v79
	ds_write_b16 v91, v69 offset:24560
	ds_write_b16_d16_hi v91, v69 offset:58352
	v_mul_f32_e32 v69, v65, v79
	v_lshl_add_u64 v[78:79], s[68:69], 0, v[62:63]
	v_add_co_u32_e32 v78, vcc, s0, v78
	v_cvt_pk_bf16_f32 v69, v69, 0
	s_nop 0
	v_addc_co_u32_e32 v79, vcc, 0, v79, vcc
	v_lshl_or_b32 v107, v69, 16, v67
	flat_store_dwordx4 v[78:79], v[0:3]
	flat_store_dwordx4 v[78:79], v[4:7] offset:16
	flat_store_dwordx4 v[78:79], v[8:11] offset:32
	flat_store_dwordx4 v[78:79], v[104:107] offset:48
	s_and_saveexec_b64 s[0:1], s[42:43]
	s_cbranch_execz .LBB0_448
	v_lshl_add_u64 v[0:1], s[68:69], 0, v[60:61]
	flat_store_dword v[0:1], v65
